# lever 2: Wo(L1)/down epilogues issue 7 of 8 second-batch residual loads two sections earlier into dead registers (sections 5-8 read them there)
# speedup vs baseline: 1.0012x; 1.0012x over previous
; #define PG8_LAS __attribute__((address_space(3)))
;     __device__ __forceinline__ void operator()(const f32x4 (&acc)[2][2][4][2], const Unit& u, int ui, int wr, int wc, int fr, int fq) const {
;     ...
;         for (int ai = 0; ai < 2; ++ai) {
;         bf16x8 rr[4][2];
;         if (MODE == 2) {
; #pragma unroll
;             for (int m = 0; m < 4; ++m)
; #pragma unroll
;                 for (int bj = 0; bj < 2; ++bj) rr[m][bj] = *(const bf16x8*)(R + (size_t)(row0 + ai * HALF + m * 16) * ldc + col0 + bj * HALF);
;             __builtin_amdgcn_sched_barrier(0); }
; #pragma unroll
;             for (int m = 0; m < 4; ++m) { const int row = row0 + ai * HALF + m * 16; const size_t off = (size_t)row * ldc + col0;
;                 float mu = 0.f, rs = 1.f; if (FOLD) { const f32x2_t ms = ((const PG8_LAS f32x2_t*)tb)[pslot + ai * HALF + wr * 64 + m * 16 + fr]; mu = ms.x; rs = ms.y; }
;                 float ssum = 0.f, ssq = 0.f;
; #pragma unroll
;                 for (int bj = 0; bj < 2; ++bj) { f32x4 v0 = acc[ai][bj][m][0], v1 = acc[ai][bj][m][1];
;                     if (FOLD && MODE != 2) { v0 = (v0 - mu * cv[bj][0]) * rs + bv[bj][0]; v1 = (v1 - mu * cv[bj][1]) * rs + bv[bj][1]; }
;                     if (MODE == 0) { v0 = v0 * sc; v1 = v1 * sc; }
;                     if (MODE == 1) { v0 = __builtin_elementwise_max(v0, (f32x4){0.f, 0.f, 0.f, 0.f}); v1 = __builtin_elementwise_max(v1, (f32x4){0.f, 0.f, 0.f, 0.f}); v0 = v0 * v0; v1 = v1 * v1; }
;                     if (MODE == 2) { const bf16x8 r = rr[m][bj];
;                         f32x4 h0 = (f32x4){(float)r[0], (float)r[1], (float)r[2], (float)r[3]}, h1 = (f32x4){(float)r[4], (float)r[5], (float)r[6], (float)r[7]};
;                         if (FOLD) { h0 = (h0 - mu) * rs * cv[bj][0] + bv[bj][0]; h1 = (h1 - mu) * rs * cv[bj][1] + bv[bj][1]; }
;                         v0 = v0 + alpha * h0; v1 = v1 + alpha * h1;
;                         ssum += (v0[0] + v0[1]) + (v0[2] + v0[3]) + (v1[0] + v1[1]) + (v1[2] + v1[3]);
;                         ssq += (v0[0] * v0[0] + v0[1] * v0[1]) + (v0[2] * v0[2] + v0[3] * v0[3]) + (v1[0] * v1[0] + v1[1] * v1[1]) + (v1[2] * v1[2] + v1[3] * v1[3]); }
;                     u32x4 w; w.x = pk2h(v0[0], v0[1]); w.y = pk2h(v0[2], v0[3]); w.z = pk2h(v1[0], v1[1]); w.w = pk2h(v1[2], v1[3]);
.LBB0_791:
	s_or_b64 exec, exec, s[22:23]
	v_add_u32_e32 v156, 0x80, v202
	v_ashrrev_i32_e32 v157, 31, v156
	v_lshlrev_b64 v[156:157], 11, v[156:157]
	v_lshl_add_u64 v[156:157], v[204:205], 0, v[156:157]
	global_load_dwordx4 v[208:211], v[156:157], off
	global_load_dwordx4 v[212:215], v[156:157], off offset:256
	v_add_u32_e32 v156, 0x90, v202
	v_ashrrev_i32_e32 v157, 31, v156
	v_lshlrev_b64 v[156:157], 11, v[156:157]
	v_lshl_add_u64 v[156:157], v[204:205], 0, v[156:157]
	global_load_dwordx4 v[182:185], v[156:157], off
	global_load_dwordx4 v[186:189], v[156:157], off offset:256
	v_add_u32_e32 v156, 0xa0, v202
	v_ashrrev_i32_e32 v157, 31, v156
	v_lshlrev_b64 v[156:157], 11, v[156:157]
	v_lshl_add_u64 v[156:157], v[204:205], 0, v[156:157]
	global_load_dwordx4 v[162:165], v[156:157], off
	global_load_dwordx4 v[166:169], v[156:157], off offset:256
	v_add_u32_e32 v156, 0xb0, v202
	v_ashrrev_i32_e32 v157, 31, v156
	v_lshlrev_b64 v[156:157], 11, v[156:157]
	v_lshl_add_u64 v[156:157], v[204:205], 0, v[156:157]
	global_load_dwordx4 v[154:157], v[156:157], off
	s_waitcnt lgkmcnt(0)
	ds_read_b64 v[136:137], v229 offset:256
	v_cvt_f32_f16_sdwa v1, v178 dst_sel:DWORD dst_unused:UNUSED_PAD src0_sel:WORD_1
	v_cvt_f32_f16_e32 v138, v178
	v_cvt_f32_f16_sdwa v140, v179 dst_sel:DWORD dst_unused:UNUSED_PAD src0_sel:WORD_1
	v_cvt_f32_f16_e32 v142, v179
	v_cvt_f32_f16_sdwa v143, v180 dst_sel:DWORD dst_unused:UNUSED_PAD src0_sel:WORD_1
	v_cvt_f32_f16_e32 v144, v180
	v_cvt_f32_f16_sdwa v145, v181 dst_sel:DWORD dst_unused:UNUSED_PAD src0_sel:WORD_1
	v_cvt_f32_f16_e32 v146, v181
	s_waitcnt lgkmcnt(0)
	v_sub_f32_e32 v139, v1, v136
	v_sub_f32_e32 v141, v140, v136
	v_sub_f32_e32 v138, v138, v136
	v_sub_f32_e32 v140, v142, v136
	v_pk_mul_f32 v[140:141], v[136:137], v[140:141] op_sel:[1,0]
	v_pk_mul_f32 v[138:139], v[136:137], v[138:139] op_sel:[1,0]
	v_sub_f32_e32 v143, v143, v136
	v_sub_f32_e32 v145, v145, v136
	v_sub_f32_e32 v142, v144, v136
	v_sub_f32_e32 v144, v146, v136
	v_pk_fma_f32 v[138:139], v[94:95], v[138:139], v[98:99]
	v_pk_fma_f32 v[140:141], v[96:97], v[140:141], v[100:101]
	v_pk_mul_f32 v[144:145], v[136:137], v[144:145] op_sel:[1,0]
	v_pk_mul_f32 v[142:143], v[136:137], v[142:143] op_sel:[1,0]
	v_pk_fma_f32 v[144:145], v[88:89], v[144:145], v[92:93]
	v_pk_fma_f32 v[142:143], v[86:87], v[142:143], v[90:91]
	v_pk_fma_f32 v[132:133], v[140:141], s[18:19], v[132:133] op_sel_hi:[1,0,1]
	v_pk_fma_f32 v[130:131], v[138:139], s[18:19], v[130:131] op_sel_hi:[1,0,1]
	v_pk_fma_f32 v[138:139], v[144:145], s[18:19], v[128:129] op_sel_hi:[1,0,1]
	v_pk_fma_f32 v[128:129], v[142:143], s[18:19], v[126:127] op_sel_hi:[1,0,1]
	v_pk_mov_b32 v[126:127], v[130:131], v[132:133] op_sel:[1,0]
	v_mov_b32_e32 v140, v130
	v_mov_b32_e32 v141, v133
	v_pk_add_f32 v[140:141], v[126:127], v[140:141]
	v_pk_mul_f32 v[126:127], v[132:133], v[132:133]
	v_pk_mul_f32 v[144:145], v[130:131], v[130:131]
	v_lshlrev_b64 v[134:135], 10, v[218:219]
	v_pk_mov_b32 v[146:147], v[144:145], v[126:127] op_sel:[1,0]
	v_mov_b32_e32 v145, v127
	v_pk_add_f32 v[126:127], v[146:147], v[144:145]
	v_lshl_add_u64 v[134:135], v[134:135], 1, v[200:201]
	v_pk_add_f32 v[144:145], v[126:127], v[126:127] op_sel_hi:[0,1]
	v_mul_f32_e32 v126, v128, v128
	v_add_f32_e32 v142, v128, v129
	v_pk_fma_f32 v[146:147], v[128:129], v[128:129], v[126:127] op_sel_hi:[1,1,0]
	v_cvt_pk_f16_f32 v126, v130, v131
	v_cvt_pk_f16_f32 v127, v132, v133
	v_cvt_pk_f16_f32 v128, v128, v129
	v_cvt_pk_f16_f32 v129, v138, v139
	global_store_dwordx4 v[134:135], v[126:129], off
	v_cvt_f32_f16_e32 v130, v175
	v_cvt_f32_f16_sdwa v131, v176 dst_sel:DWORD dst_unused:UNUSED_PAD src0_sel:WORD_1
	v_cvt_f32_f16_sdwa v126, v174 dst_sel:DWORD dst_unused:UNUSED_PAD src0_sel:WORD_1
	v_cvt_f32_f16_e32 v128, v174
	v_cvt_f32_f16_sdwa v129, v175 dst_sel:DWORD dst_unused:UNUSED_PAD src0_sel:WORD_1
	v_cvt_f32_f16_e32 v132, v176
	v_cvt_f32_f16_sdwa v133, v177 dst_sel:DWORD dst_unused:UNUSED_PAD src0_sel:WORD_1
	v_cvt_f32_f16_e32 v143, v177
	v_sub_f32_e32 v127, v126, v136
	v_sub_f32_e32 v129, v129, v136
	v_sub_f32_e32 v126, v128, v136
	v_sub_f32_e32 v128, v130, v136
	v_pk_mul_f32 v[128:129], v[136:137], v[128:129] op_sel:[1,0]
	v_pk_mul_f32 v[126:127], v[136:137], v[126:127] op_sel:[1,0]
	v_sub_f32_e32 v131, v131, v136
	v_sub_f32_e32 v133, v133, v136
	v_sub_f32_e32 v130, v132, v136
	v_sub_f32_e32 v132, v143, v136
	v_pk_fma_f32 v[126:127], v[78:79], v[126:127], v[82:83]
	v_pk_fma_f32 v[128:129], v[80:81], v[128:129], v[84:85]
	v_pk_mul_f32 v[132:133], v[136:137], v[132:133] op_sel:[1,0]
	v_pk_mul_f32 v[130:131], v[136:137], v[130:131] op_sel:[1,0]
	v_pk_fma_f32 v[132:133], v[68:69], v[132:133], v[76:77]
	v_pk_fma_f32 v[130:131], v[66:67], v[130:131], v[74:75]
	v_pk_fma_f32 v[124:125], v[128:129], s[18:19], v[124:125] op_sel_hi:[1,0,1]
	v_pk_fma_f32 v[122:123], v[126:127], s[18:19], v[122:123] op_sel_hi:[1,0,1]
	v_pk_fma_f32 v[126:127], v[132:133], s[18:19], v[120:121] op_sel_hi:[1,0,1]
	v_pk_fma_f32 v[120:121], v[130:131], s[18:19], v[118:119] op_sel_hi:[1,0,1]
	v_pk_mov_b32 v[118:119], v[122:123], v[124:125] op_sel:[1,0]
	v_mov_b32_e32 v128, v122
	v_mov_b32_e32 v129, v125
	v_pk_add_f32 v[128:129], v[118:119], v[128:129]
	v_mul_f32_e32 v118, v122, v122
	v_pk_fma_f32 v[130:131], v[122:123], v[122:123], v[118:119] op_sel_hi:[1,1,0]
	v_mul_f32_e32 v118, v124, v124
	v_pk_fma_f32 v[132:133], v[124:125], v[124:125], v[118:119] op_sel_hi:[1,1,0]
	v_mul_f32_e32 v118, v126, v126
	v_add_f32_e32 v148, v120, v121
	v_mul_f32_e32 v143, v120, v120
	v_mul_f32_e32 v150, v121, v121
	v_pk_fma_f32 v[136:137], v[126:127], v[126:127], v[118:119] op_sel_hi:[1,1,0]
	v_cvt_pk_f16_f32 v118, v122, v123
	v_cvt_pk_f16_f32 v119, v124, v125
	v_cvt_pk_f16_f32 v120, v120, v121
	v_cvt_pk_f16_f32 v121, v126, v127
	v_mul_f32_e32 v1, v139, v139
	global_store_dwordx4 v[134:135], v[118:121], off offset:256
	v_mul_f32_e32 v149, v138, v138
	v_mov_b32_e32 v146, v126
	v_pk_add_f32 v[118:119], v[128:129], v[128:129] op_sel:[0,1] op_sel_hi:[1,0]
	v_mov_b32_e32 v144, v127
	v_mov_b32_e32 v119, v1
	v_pk_add_f32 v[122:123], v[140:141], v[140:141] op_sel:[0,1] op_sel_hi:[1,0]
	v_pk_add_f32 v[118:119], v[148:149], v[118:119]
	v_pk_add_f32 v[120:121], v[146:147], v[144:145]
	v_mov_b32_e32 v130, v138
	v_mov_b32_e32 v132, v139
	v_mov_b32_e32 v123, v150
	v_pk_add_f32 v[118:119], v[118:119], v[120:121]
	v_pk_add_f32 v[120:121], v[130:131], v[132:133]
	v_pk_add_f32 v[122:123], v[142:143], v[122:123]
	v_mov_b32_e32 v1, v137
	v_pk_add_f32 v[120:121], v[122:123], v[120:121]
	s_nop 0
	v_pk_add_f32 v[120:121], v[120:121], v[0:1]
	s_nop 0
	v_pk_add_f32 v[118:119], v[118:119], v[120:121]
	ds_bpermute_b32 v120, v228, v118
	ds_bpermute_b32 v121, v228, v119
	s_waitcnt lgkmcnt(0)
	v_pk_add_f32 v[118:119], v[118:119], v[120:121]
	ds_bpermute_b32 v120, v227, v118
	ds_bpermute_b32 v121, v227, v119
	s_and_saveexec_b64 s[22:23], s[36:37]
	v_readlane_b32 s54, v255, 25
	v_readlane_b32 s55, v255, 26
	s_cbranch_execz .LBB0_793
;     __device__ __forceinline__ void operator()(const f32x4 (&acc)[2][2][4][2], const Unit& u, int ui, int wr, int wc, int fr, int fq) const {
;     ...
;                 if (MODE == 2) { ssum += __shfl_xor(ssum, 16); ssq += __shfl_xor(ssq, 16); ssum += __shfl_xor(ssum, 32); ssq += __shfl_xor(ssq, 32);
;                     if (fq == 0) part[(size_t)(row0 + ai * HALF + m * 16) * 16 + u.pn * 4 + wc] = (f32x2_t){ssum, ssq}; } }
	s_waitcnt lgkmcnt(0)
	v_pk_add_f32 v[118:119], v[118:119], v[120:121]
	v_lshlrev_b64 v[120:121], 7, v[218:219]
	v_lshl_add_u64 v[120:121], s[0:1], 0, v[120:121]
	v_lshl_add_u64 v[120:121], s[16:17], 3, v[120:121]
	s_lshl_b32 s58, s72, 3
	v_lshl_add_u64 v[120:121], v[120:121], 0, s[58:59]
	global_store_dwordx2 v[120:121], v[118:119], off

; #define PG8_LAS __attribute__((address_space(3)))
;     __device__ __forceinline__ void operator()(const f32x4 (&acc)[2][2][4][2], const Unit& u, int ui, int wr, int wc, int fr, int fq) const {
;     ...
;                 for (int bj = 0; bj < 2; ++bj) rr[m][bj] = *(const bf16x8*)(R + (size_t)(row0 + ai * HALF + m * 16) * ldc + col0 + bj * HALF);
;             __builtin_amdgcn_sched_barrier(0); }
; #pragma unroll
;             for (int m = 0; m < 4; ++m) { const int row = row0 + ai * HALF + m * 16; const size_t off = (size_t)row * ldc + col0;
;                 float mu = 0.f, rs = 1.f; if (FOLD) { const f32x2_t ms = ((const PG8_LAS f32x2_t*)tb)[pslot + ai * HALF + wr * 64 + m * 16 + fr]; mu = ms.x; rs = ms.y; }
;                 float ssum = 0.f, ssq = 0.f;
; #pragma unroll
;                 for (int bj = 0; bj < 2; ++bj) { f32x4 v0 = acc[ai][bj][m][0], v1 = acc[ai][bj][m][1];
;                     if (FOLD && MODE != 2) { v0 = (v0 - mu * cv[bj][0]) * rs + bv[bj][0]; v1 = (v1 - mu * cv[bj][1]) * rs + bv[bj][1]; }
;                     if (MODE == 0) { v0 = v0 * sc; v1 = v1 * sc; }
;                     if (MODE == 1) { v0 = __builtin_elementwise_max(v0, (f32x4){0.f, 0.f, 0.f, 0.f}); v1 = __builtin_elementwise_max(v1, (f32x4){0.f, 0.f, 0.f, 0.f}); v0 = v0 * v0; v1 = v1 * v1; }
;                     if (MODE == 2) { const bf16x8 r = rr[m][bj];
;                         f32x4 h0 = (f32x4){(float)r[0], (float)r[1], (float)r[2], (float)r[3]}, h1 = (f32x4){(float)r[4], (float)r[5], (float)r[6], (float)r[7]};
;                         if (FOLD) { h0 = (h0 - mu) * rs * cv[bj][0] + bv[bj][0]; h1 = (h1 - mu) * rs * cv[bj][1] + bv[bj][1]; }
;                         v0 = v0 + alpha * h0; v1 = v1 + alpha * h1;
;                         ssum += (v0[0] + v0[1]) + (v0[2] + v0[3]) + (v1[0] + v1[1]) + (v1[2] + v1[3]);
;                         ssq += (v0[0] * v0[0] + v0[1] * v0[1]) + (v0[2] * v0[2] + v0[3] * v0[3]) + (v1[0] * v1[0] + v1[1] * v1[1]) + (v1[2] * v1[2] + v1[3] * v1[3]); }
;                     u32x4 w; w.x = pk2h(v0[0], v0[1]); w.y = pk2h(v0[2], v0[3]); w.z = pk2h(v1[0], v1[1]); w.w = pk2h(v1[2], v1[3]);
;                     if (MODE == 0 && hm) { const int cc = col0 + bj * HALF; *(u32x4*)(base + ((size_t)(row >> 11) * 16 + (cc >> 6)) * 131072 + (size_t)(row & 2047) * 64 + (cc & 63)) = w; }
;                     else *(u32x4*)(base + off + bj * HALF) = w; }
.LBB0_795:
	s_or_b64 exec, exec, s[22:23]
	v_add_u32_e32 v132, 0x80, v202
	v_ashrrev_i32_e32 v133, 31, v132
	v_lshlrev_b64 v[142:143], 11, v[132:133]
	v_add_u32_e32 v130, 0x90, v202
	v_lshl_add_u64 v[102:103], v[204:205], 0, v[142:143]
	v_ashrrev_i32_e32 v131, 31, v130
	v_lshlrev_b64 v[102:103], 11, v[130:131]
	v_add_u32_e32 v128, 0xa0, v202
	v_lshl_add_u64 v[102:103], v[204:205], 0, v[102:103]
	v_ashrrev_i32_e32 v129, 31, v128
	v_lshlrev_b64 v[102:103], 11, v[128:129]
	v_add_u32_e32 v126, 0xb0, v202
	v_lshl_add_u64 v[102:103], v[204:205], 0, v[102:103]
	v_ashrrev_i32_e32 v127, 31, v126
	v_lshlrev_b64 v[102:103], 11, v[126:127]
	v_lshl_add_u64 v[102:103], v[204:205], 0, v[102:103]
	s_waitcnt lgkmcnt(0)
	global_load_dwordx4 v[102:105], v[102:103], off offset:256
	ds_read_b64 v[144:145], v229 offset:1024
	s_waitcnt vmcnt(7)
	v_cvt_f32_f16_sdwa v1, v208 dst_sel:DWORD dst_unused:UNUSED_PAD src0_sel:WORD_1
	v_cvt_f32_f16_e32 v134, v208
	v_cvt_f32_f16_sdwa v146, v209 dst_sel:DWORD dst_unused:UNUSED_PAD src0_sel:WORD_1
	v_cvt_f32_f16_e32 v147, v209
	v_cvt_f32_f16_sdwa v148, v210 dst_sel:DWORD dst_unused:UNUSED_PAD src0_sel:WORD_1
	v_cvt_f32_f16_e32 v149, v210
	v_cvt_f32_f16_sdwa v150, v211 dst_sel:DWORD dst_unused:UNUSED_PAD src0_sel:WORD_1
	v_cvt_f32_f16_e32 v151, v211
	s_waitcnt lgkmcnt(0)
	v_sub_f32_e32 v134, v134, v144
	v_sub_f32_e32 v135, v1, v144
	v_sub_f32_e32 v136, v147, v144
	v_sub_f32_e32 v137, v146, v144
	v_pk_mul_f32 v[136:137], v[144:145], v[136:137] op_sel:[1,0]
	v_pk_mul_f32 v[134:135], v[144:145], v[134:135] op_sel:[1,0]
	v_sub_f32_e32 v146, v149, v144
	v_sub_f32_e32 v147, v148, v144
	v_sub_f32_e32 v148, v151, v144
	v_sub_f32_e32 v149, v150, v144
	v_pk_fma_f32 v[134:135], v[94:95], v[134:135], v[98:99]
	v_pk_fma_f32 v[136:137], v[96:97], v[136:137], v[100:101]
	v_pk_mul_f32 v[148:149], v[144:145], v[148:149] op_sel:[1,0]
	v_pk_mul_f32 v[146:147], v[144:145], v[146:147] op_sel:[1,0]
	v_pk_fma_f32 v[148:149], v[88:89], v[148:149], v[92:93]
	v_pk_fma_f32 v[146:147], v[86:87], v[146:147], v[90:91]
	v_pk_fma_f32 v[72:73], v[136:137], s[18:19], v[72:73] op_sel_hi:[1,0,1]
	v_pk_fma_f32 v[70:71], v[134:135], s[18:19], v[70:71] op_sel_hi:[1,0,1]
	v_pk_fma_f32 v[134:135], v[148:149], s[18:19], v[64:65] op_sel_hi:[1,0,1]
	v_pk_fma_f32 v[64:65], v[146:147], s[18:19], v[62:63] op_sel_hi:[1,0,1]
	v_pk_mov_b32 v[62:63], v[70:71], v[72:73] op_sel:[1,0]
	v_mov_b32_e32 v136, v70
	v_mov_b32_e32 v137, v73
	v_pk_add_f32 v[136:137], v[62:63], v[136:137]
	v_pk_mul_f32 v[62:63], v[72:73], v[72:73]
	v_pk_mul_f32 v[148:149], v[70:71], v[70:71]
	v_lshl_add_u64 v[142:143], v[200:201], 0, v[142:143]
	v_pk_mov_b32 v[150:151], v[148:149], v[62:63] op_sel:[1,0]
	v_mov_b32_e32 v149, v63
	v_pk_add_f32 v[62:63], v[150:151], v[148:149]
	v_add_f32_e32 v146, v64, v65
	v_pk_add_f32 v[148:149], v[62:63], v[62:63] op_sel_hi:[0,1]
	v_mul_f32_e32 v62, v64, v64
	v_pk_fma_f32 v[150:151], v[64:65], v[64:65], v[62:63] op_sel_hi:[1,1,0]
	v_cvt_pk_f16_f32 v62, v70, v71
	v_cvt_pk_f16_f32 v63, v72, v73
	v_cvt_pk_f16_f32 v64, v64, v65
	v_cvt_pk_f16_f32 v65, v134, v135
	global_store_dwordx4 v[142:143], v[62:65], off
	s_waitcnt vmcnt(7)
	v_cvt_f32_f16_sdwa v71, v214 dst_sel:DWORD dst_unused:UNUSED_PAD src0_sel:WORD_1
	v_cvt_f32_f16_e32 v70, v214
	v_cvt_f32_f16_sdwa v63, v212 dst_sel:DWORD dst_unused:UNUSED_PAD src0_sel:WORD_1
	v_cvt_f32_f16_e32 v62, v212
	v_cvt_f32_f16_sdwa v65, v213 dst_sel:DWORD dst_unused:UNUSED_PAD src0_sel:WORD_1
	v_cvt_f32_f16_e32 v64, v213
	v_cvt_f32_f16_sdwa v73, v215 dst_sel:DWORD dst_unused:UNUSED_PAD src0_sel:WORD_1
	v_cvt_f32_f16_e32 v72, v215
	v_sub_f32_e32 v62, v62, v144
	v_sub_f32_e32 v63, v63, v144
	v_sub_f32_e32 v64, v64, v144
	v_sub_f32_e32 v65, v65, v144
	v_pk_mul_f32 v[64:65], v[144:145], v[64:65] op_sel:[1,0]
	v_pk_mul_f32 v[62:63], v[144:145], v[62:63] op_sel:[1,0]
	v_sub_f32_e32 v70, v70, v144
	v_sub_f32_e32 v71, v71, v144
	v_sub_f32_e32 v72, v72, v144
	v_sub_f32_e32 v73, v73, v144
	v_pk_fma_f32 v[62:63], v[78:79], v[62:63], v[82:83]
	v_pk_fma_f32 v[64:65], v[80:81], v[64:65], v[84:85]
	v_pk_mul_f32 v[72:73], v[144:145], v[72:73] op_sel:[1,0]
	v_pk_mul_f32 v[70:71], v[144:145], v[70:71] op_sel:[1,0]
	v_pk_fma_f32 v[72:73], v[68:69], v[72:73], v[76:77]
	v_pk_fma_f32 v[70:71], v[66:67], v[70:71], v[74:75]
	v_pk_fma_f32 v[60:61], v[64:65], s[18:19], v[60:61] op_sel_hi:[1,0,1]
	v_pk_fma_f32 v[58:59], v[62:63], s[18:19], v[58:59] op_sel_hi:[1,0,1]
	v_pk_fma_f32 v[62:63], v[72:73], s[18:19], v[56:57] op_sel_hi:[1,0,1]
	v_pk_fma_f32 v[56:57], v[70:71], s[18:19], v[54:55] op_sel_hi:[1,0,1]
	v_pk_mov_b32 v[54:55], v[58:59], v[60:61] op_sel:[1,0]
	v_mov_b32_e32 v64, v58
	v_mov_b32_e32 v65, v61
	v_pk_add_f32 v[64:65], v[54:55], v[64:65]
	v_mul_f32_e32 v54, v58, v58
	v_pk_fma_f32 v[70:71], v[58:59], v[58:59], v[54:55] op_sel_hi:[1,1,0]
	v_mul_f32_e32 v54, v60, v60
	v_pk_fma_f32 v[72:73], v[60:61], v[60:61], v[54:55] op_sel_hi:[1,1,0]
	v_mul_f32_e32 v54, v62, v62
	v_add_f32_e32 v152, v56, v57
	v_mul_f32_e32 v147, v56, v56
	v_mul_f32_e32 v140, v57, v57
	v_pk_fma_f32 v[138:139], v[62:63], v[62:63], v[54:55] op_sel_hi:[1,1,0]
	v_cvt_pk_f16_f32 v54, v58, v59
	v_cvt_pk_f16_f32 v55, v60, v61
	v_cvt_pk_f16_f32 v56, v56, v57
	v_cvt_pk_f16_f32 v57, v62, v63
	v_mul_f32_e32 v1, v135, v135
	global_store_dwordx4 v[142:143], v[54:57], off offset:256
	v_mul_f32_e32 v153, v134, v134
	v_mov_b32_e32 v150, v62
	v_pk_add_f32 v[54:55], v[64:65], v[64:65] op_sel:[0,1] op_sel_hi:[1,0]
	v_mov_b32_e32 v148, v63
	v_mov_b32_e32 v55, v1
	v_pk_add_f32 v[58:59], v[136:137], v[136:137] op_sel:[0,1] op_sel_hi:[1,0]
	v_pk_add_f32 v[54:55], v[152:153], v[54:55]
	v_pk_add_f32 v[56:57], v[150:151], v[148:149]
	v_mov_b32_e32 v70, v134
	v_mov_b32_e32 v72, v135
	v_mov_b32_e32 v59, v140
	v_pk_add_f32 v[54:55], v[54:55], v[56:57]
	v_pk_add_f32 v[56:57], v[70:71], v[72:73]
	v_pk_add_f32 v[58:59], v[146:147], v[58:59]
	v_mov_b32_e32 v1, v139
	v_pk_add_f32 v[56:57], v[58:59], v[56:57]
	s_nop 0
	v_pk_add_f32 v[56:57], v[56:57], v[0:1]
	s_nop 0
	v_pk_add_f32 v[54:55], v[54:55], v[56:57]
	ds_bpermute_b32 v56, v228, v54
	ds_bpermute_b32 v57, v228, v55
	s_waitcnt lgkmcnt(0)
	v_pk_add_f32 v[54:55], v[54:55], v[56:57]
	ds_bpermute_b32 v56, v227, v54
	ds_bpermute_b32 v57, v227, v55
	s_and_saveexec_b64 s[22:23], s[36:37]
	s_cbranch_execz .LBB0_797
	s_waitcnt lgkmcnt(0)
	v_pk_add_f32 v[54:55], v[54:55], v[56:57]
	v_lshlrev_b64 v[56:57], 7, v[132:133]
	v_lshl_add_u64 v[56:57], s[0:1], 0, v[56:57]
	v_lshl_add_u64 v[56:57], s[16:17], 3, v[56:57]
	s_lshl_b32 s58, s72, 3
	v_lshl_add_u64 v[56:57], v[56:57], 0, s[58:59]
	global_store_dwordx2 v[56:57], v[54:55], off
; #define PG8_LAS __attribute__((address_space(3)))
;     __device__ __forceinline__ void operator()(const f32x4 (&acc)[2][2][4][2], const Unit& u, int ui, int wr, int wc, int fr, int fq) const {
;     ...
;                 for (int bj = 0; bj < 2; ++bj) rr[m][bj] = *(const bf16x8*)(R + (size_t)(row0 + ai * HALF + m * 16) * ldc + col0 + bj * HALF);
;             __builtin_amdgcn_sched_barrier(0); }
; #pragma unroll
;             for (int m = 0; m < 4; ++m) { const int row = row0 + ai * HALF + m * 16; const size_t off = (size_t)row * ldc + col0;
;                 float mu = 0.f, rs = 1.f; if (FOLD) { const f32x2_t ms = ((const PG8_LAS f32x2_t*)tb)[pslot + ai * HALF + wr * 64 + m * 16 + fr]; mu = ms.x; rs = ms.y; }
;                 float ssum = 0.f, ssq = 0.f;
; #pragma unroll
;                 for (int bj = 0; bj < 2; ++bj) { f32x4 v0 = acc[ai][bj][m][0], v1 = acc[ai][bj][m][1];
;                     if (FOLD && MODE != 2) { v0 = (v0 - mu * cv[bj][0]) * rs + bv[bj][0]; v1 = (v1 - mu * cv[bj][1]) * rs + bv[bj][1]; }
;                     if (MODE == 0) { v0 = v0 * sc; v1 = v1 * sc; }
;                     if (MODE == 1) { v0 = __builtin_elementwise_max(v0, (f32x4){0.f, 0.f, 0.f, 0.f}); v1 = __builtin_elementwise_max(v1, (f32x4){0.f, 0.f, 0.f, 0.f}); v0 = v0 * v0; v1 = v1 * v1; }
;                     if (MODE == 2) { const bf16x8 r = rr[m][bj];
;                         f32x4 h0 = (f32x4){(float)r[0], (float)r[1], (float)r[2], (float)r[3]}, h1 = (f32x4){(float)r[4], (float)r[5], (float)r[6], (float)r[7]};
;                         if (FOLD) { h0 = (h0 - mu) * rs * cv[bj][0] + bv[bj][0]; h1 = (h1 - mu) * rs * cv[bj][1] + bv[bj][1]; }
;                         v0 = v0 + alpha * h0; v1 = v1 + alpha * h1;
;                         ssum += (v0[0] + v0[1]) + (v0[2] + v0[3]) + (v1[0] + v1[1]) + (v1[2] + v1[3]);
;                         ssq += (v0[0] * v0[0] + v0[1] * v0[1]) + (v0[2] * v0[2] + v0[3] * v0[3]) + (v1[0] * v1[0] + v1[1] * v1[1]) + (v1[2] * v1[2] + v1[3] * v1[3]); }
;                     u32x4 w; w.x = pk2h(v0[0], v0[1]); w.y = pk2h(v0[2], v0[3]); w.z = pk2h(v1[0], v1[1]); w.w = pk2h(v1[2], v1[3]);
;                     if (MODE == 0 && hm) { const int cc = col0 + bj * HALF; *(u32x4*)(base + ((size_t)(row >> 11) * 16 + (cc >> 6)) * 131072 + (size_t)(row & 2047) * 64 + (cc & 63)) = w; }
;                     else *(u32x4*)(base + off + bj * HALF) = w; }
.LBB0_797:
	s_or_b64 exec, exec, s[22:23]
	s_waitcnt lgkmcnt(0)
	ds_read_b64 v[56:57], v229 offset:1152
	s_waitcnt vmcnt(7)
	v_cvt_f32_f16_sdwa v1, v182 dst_sel:DWORD dst_unused:UNUSED_PAD src0_sel:WORD_1
	v_cvt_f32_f16_e32 v58, v182
	v_cvt_f32_f16_sdwa v60, v183 dst_sel:DWORD dst_unused:UNUSED_PAD src0_sel:WORD_1
	v_cvt_f32_f16_e32 v62, v183
	v_cvt_f32_f16_sdwa v63, v184 dst_sel:DWORD dst_unused:UNUSED_PAD src0_sel:WORD_1
	v_cvt_f32_f16_e32 v64, v184
	v_cvt_f32_f16_sdwa v65, v185 dst_sel:DWORD dst_unused:UNUSED_PAD src0_sel:WORD_1
	v_cvt_f32_f16_e32 v70, v185
	s_waitcnt lgkmcnt(0)
	v_sub_f32_e32 v59, v1, v56
	v_sub_f32_e32 v61, v60, v56
	v_sub_f32_e32 v58, v58, v56
	v_sub_f32_e32 v60, v62, v56
	v_pk_mul_f32 v[60:61], v[56:57], v[60:61] op_sel:[1,0]
	v_pk_mul_f32 v[58:59], v[56:57], v[58:59] op_sel:[1,0]
	v_sub_f32_e32 v63, v63, v56
	v_sub_f32_e32 v65, v65, v56
	v_sub_f32_e32 v62, v64, v56
	v_sub_f32_e32 v64, v70, v56
	v_pk_fma_f32 v[58:59], v[94:95], v[58:59], v[98:99]
	v_pk_fma_f32 v[60:61], v[96:97], v[60:61], v[100:101]
	v_pk_mul_f32 v[64:65], v[56:57], v[64:65] op_sel:[1,0]
	v_pk_mul_f32 v[62:63], v[56:57], v[62:63] op_sel:[1,0]
	v_pk_fma_f32 v[64:65], v[88:89], v[64:65], v[92:93]
	v_pk_fma_f32 v[62:63], v[86:87], v[62:63], v[90:91]
	v_pk_fma_f32 v[52:53], v[60:61], s[18:19], v[52:53] op_sel_hi:[1,0,1]
	v_pk_fma_f32 v[50:51], v[58:59], s[18:19], v[50:51] op_sel_hi:[1,0,1]
	v_pk_fma_f32 v[58:59], v[64:65], s[18:19], v[48:49] op_sel_hi:[1,0,1]
	v_pk_fma_f32 v[48:49], v[62:63], s[18:19], v[46:47] op_sel_hi:[1,0,1]
	v_pk_mov_b32 v[46:47], v[50:51], v[52:53] op_sel:[1,0]
	v_mov_b32_e32 v60, v50
	v_mov_b32_e32 v61, v53
	v_pk_add_f32 v[60:61], v[46:47], v[60:61]
	v_pk_mul_f32 v[46:47], v[52:53], v[52:53]
	v_pk_mul_f32 v[64:65], v[50:51], v[50:51]
	v_lshlrev_b64 v[54:55], 10, v[130:131]
	v_pk_mov_b32 v[70:71], v[64:65], v[46:47] op_sel:[1,0]
	v_mov_b32_e32 v65, v47
	v_pk_add_f32 v[46:47], v[70:71], v[64:65]
	v_lshl_add_u64 v[54:55], v[54:55], 1, v[200:201]
	v_pk_add_f32 v[64:65], v[46:47], v[46:47] op_sel_hi:[0,1]
	v_mul_f32_e32 v46, v48, v48
	v_add_f32_e32 v62, v48, v49
	v_pk_fma_f32 v[70:71], v[48:49], v[48:49], v[46:47] op_sel_hi:[1,1,0]
	v_cvt_pk_f16_f32 v46, v50, v51
	v_cvt_pk_f16_f32 v47, v52, v53
	v_cvt_pk_f16_f32 v48, v48, v49
	v_cvt_pk_f16_f32 v49, v58, v59
	global_store_dwordx4 v[54:55], v[46:49], off
	s_waitcnt vmcnt(7)
	v_cvt_f32_f16_e32 v50, v187
	v_cvt_f32_f16_sdwa v51, v188 dst_sel:DWORD dst_unused:UNUSED_PAD src0_sel:WORD_1
	v_cvt_f32_f16_sdwa v46, v186 dst_sel:DWORD dst_unused:UNUSED_PAD src0_sel:WORD_1
	v_cvt_f32_f16_e32 v48, v186
	v_cvt_f32_f16_sdwa v49, v187 dst_sel:DWORD dst_unused:UNUSED_PAD src0_sel:WORD_1
	v_cvt_f32_f16_e32 v52, v188
	v_cvt_f32_f16_sdwa v53, v189 dst_sel:DWORD dst_unused:UNUSED_PAD src0_sel:WORD_1
	v_cvt_f32_f16_e32 v63, v189
	v_sub_f32_e32 v47, v46, v56
	v_sub_f32_e32 v49, v49, v56
	v_sub_f32_e32 v46, v48, v56
	v_sub_f32_e32 v48, v50, v56
	v_pk_mul_f32 v[48:49], v[56:57], v[48:49] op_sel:[1,0]
	v_pk_mul_f32 v[46:47], v[56:57], v[46:47] op_sel:[1,0]
	v_sub_f32_e32 v51, v51, v56
	v_sub_f32_e32 v53, v53, v56
	v_sub_f32_e32 v50, v52, v56
	v_sub_f32_e32 v52, v63, v56
	v_pk_fma_f32 v[46:47], v[78:79], v[46:47], v[82:83]
	v_pk_fma_f32 v[48:49], v[80:81], v[48:49], v[84:85]
	v_pk_mul_f32 v[52:53], v[56:57], v[52:53] op_sel:[1,0]
	v_pk_mul_f32 v[50:51], v[56:57], v[50:51] op_sel:[1,0]
	v_pk_fma_f32 v[52:53], v[68:69], v[52:53], v[76:77]
	v_pk_fma_f32 v[50:51], v[66:67], v[50:51], v[74:75]
	v_pk_fma_f32 v[44:45], v[48:49], s[18:19], v[44:45] op_sel_hi:[1,0,1]
	v_pk_fma_f32 v[42:43], v[46:47], s[18:19], v[42:43] op_sel_hi:[1,0,1]
	v_pk_fma_f32 v[46:47], v[52:53], s[18:19], v[40:41] op_sel_hi:[1,0,1]
	v_pk_fma_f32 v[40:41], v[50:51], s[18:19], v[38:39] op_sel_hi:[1,0,1]
	v_pk_mov_b32 v[38:39], v[42:43], v[44:45] op_sel:[1,0]
	v_mov_b32_e32 v48, v42
	v_mov_b32_e32 v49, v45
	v_pk_add_f32 v[48:49], v[38:39], v[48:49]
	v_mul_f32_e32 v38, v42, v42
	v_pk_fma_f32 v[50:51], v[42:43], v[42:43], v[38:39] op_sel_hi:[1,1,0]
	v_mul_f32_e32 v38, v44, v44
	v_pk_fma_f32 v[52:53], v[44:45], v[44:45], v[38:39] op_sel_hi:[1,1,0]
	v_mul_f32_e32 v38, v46, v46
	v_add_f32_e32 v72, v40, v41
	v_mul_f32_e32 v63, v40, v40
	v_mul_f32_e32 v118, v41, v41
	v_pk_fma_f32 v[56:57], v[46:47], v[46:47], v[38:39] op_sel_hi:[1,1,0]
	v_cvt_pk_f16_f32 v38, v42, v43
	v_cvt_pk_f16_f32 v39, v44, v45
	v_cvt_pk_f16_f32 v40, v40, v41
	v_cvt_pk_f16_f32 v41, v46, v47
	v_mul_f32_e32 v1, v59, v59
	global_store_dwordx4 v[54:55], v[38:41], off offset:256
	v_mul_f32_e32 v73, v58, v58
	v_mov_b32_e32 v70, v46
	v_pk_add_f32 v[38:39], v[48:49], v[48:49] op_sel:[0,1] op_sel_hi:[1,0]
	v_mov_b32_e32 v64, v47
	v_mov_b32_e32 v39, v1
	v_pk_add_f32 v[42:43], v[60:61], v[60:61] op_sel:[0,1] op_sel_hi:[1,0]
	v_pk_add_f32 v[38:39], v[72:73], v[38:39]
	v_pk_add_f32 v[40:41], v[70:71], v[64:65]
	v_mov_b32_e32 v50, v58
	v_mov_b32_e32 v52, v59
	v_mov_b32_e32 v43, v118
	v_pk_add_f32 v[38:39], v[38:39], v[40:41]
	v_pk_add_f32 v[40:41], v[50:51], v[52:53]
	v_pk_add_f32 v[42:43], v[62:63], v[42:43]
	v_mov_b32_e32 v1, v57
	v_pk_add_f32 v[40:41], v[42:43], v[40:41]
	s_nop 0
	v_pk_add_f32 v[40:41], v[40:41], v[0:1]
	s_nop 0
	v_pk_add_f32 v[38:39], v[38:39], v[40:41]
	ds_bpermute_b32 v40, v228, v38
	ds_bpermute_b32 v41, v228, v39
	s_waitcnt lgkmcnt(0)
	v_pk_add_f32 v[38:39], v[38:39], v[40:41]
	ds_bpermute_b32 v40, v227, v38
	ds_bpermute_b32 v41, v227, v39
	s_and_saveexec_b64 s[22:23], s[36:37]
	s_cbranch_execz .LBB0_799
	s_waitcnt lgkmcnt(0)
	v_pk_add_f32 v[38:39], v[38:39], v[40:41]
	v_lshlrev_b64 v[40:41], 7, v[130:131]
	v_lshl_add_u64 v[40:41], s[0:1], 0, v[40:41]
	v_lshl_add_u64 v[40:41], s[16:17], 3, v[40:41]
	s_lshl_b32 s58, s72, 3
	v_lshl_add_u64 v[40:41], v[40:41], 0, s[58:59]
	global_store_dwordx2 v[40:41], v[38:39], off
; #define PG8_LAS __attribute__((address_space(3)))
;     __device__ __forceinline__ void operator()(const f32x4 (&acc)[2][2][4][2], const Unit& u, int ui, int wr, int wc, int fr, int fq) const {
;     ...
;                 for (int bj = 0; bj < 2; ++bj) rr[m][bj] = *(const bf16x8*)(R + (size_t)(row0 + ai * HALF + m * 16) * ldc + col0 + bj * HALF);
;             __builtin_amdgcn_sched_barrier(0); }
; #pragma unroll
;             for (int m = 0; m < 4; ++m) { const int row = row0 + ai * HALF + m * 16; const size_t off = (size_t)row * ldc + col0;
;                 float mu = 0.f, rs = 1.f; if (FOLD) { const f32x2_t ms = ((const PG8_LAS f32x2_t*)tb)[pslot + ai * HALF + wr * 64 + m * 16 + fr]; mu = ms.x; rs = ms.y; }
;                 float ssum = 0.f, ssq = 0.f;
; #pragma unroll
;                 for (int bj = 0; bj < 2; ++bj) { f32x4 v0 = acc[ai][bj][m][0], v1 = acc[ai][bj][m][1];
;                     if (FOLD && MODE != 2) { v0 = (v0 - mu * cv[bj][0]) * rs + bv[bj][0]; v1 = (v1 - mu * cv[bj][1]) * rs + bv[bj][1]; }
;                     if (MODE == 0) { v0 = v0 * sc; v1 = v1 * sc; }
;                     if (MODE == 1) { v0 = __builtin_elementwise_max(v0, (f32x4){0.f, 0.f, 0.f, 0.f}); v1 = __builtin_elementwise_max(v1, (f32x4){0.f, 0.f, 0.f, 0.f}); v0 = v0 * v0; v1 = v1 * v1; }
;                     if (MODE == 2) { const bf16x8 r = rr[m][bj];
;                         f32x4 h0 = (f32x4){(float)r[0], (float)r[1], (float)r[2], (float)r[3]}, h1 = (f32x4){(float)r[4], (float)r[5], (float)r[6], (float)r[7]};
;                         if (FOLD) { h0 = (h0 - mu) * rs * cv[bj][0] + bv[bj][0]; h1 = (h1 - mu) * rs * cv[bj][1] + bv[bj][1]; }
;                         v0 = v0 + alpha * h0; v1 = v1 + alpha * h1;
;                         ssum += (v0[0] + v0[1]) + (v0[2] + v0[3]) + (v1[0] + v1[1]) + (v1[2] + v1[3]);
;                         ssq += (v0[0] * v0[0] + v0[1] * v0[1]) + (v0[2] * v0[2] + v0[3] * v0[3]) + (v1[0] * v1[0] + v1[1] * v1[1]) + (v1[2] * v1[2] + v1[3] * v1[3]); }
;                     u32x4 w; w.x = pk2h(v0[0], v0[1]); w.y = pk2h(v0[2], v0[3]); w.z = pk2h(v1[0], v1[1]); w.w = pk2h(v1[2], v1[3]);
;                     if (MODE == 0 && hm) { const int cc = col0 + bj * HALF; *(u32x4*)(base + ((size_t)(row >> 11) * 16 + (cc >> 6)) * 131072 + (size_t)(row & 2047) * 64 + (cc & 63)) = w; }
;                     else *(u32x4*)(base + off + bj * HALF) = w; }
.LBB0_799:
	s_or_b64 exec, exec, s[22:23]
	s_waitcnt lgkmcnt(0)
	ds_read_b64 v[40:41], v229 offset:1280
	s_waitcnt vmcnt(7)
	v_cvt_f32_f16_sdwa v1, v162 dst_sel:DWORD dst_unused:UNUSED_PAD src0_sel:WORD_1
	v_cvt_f32_f16_e32 v42, v162
	v_cvt_f32_f16_sdwa v44, v163 dst_sel:DWORD dst_unused:UNUSED_PAD src0_sel:WORD_1
	v_cvt_f32_f16_e32 v46, v163
	v_cvt_f32_f16_sdwa v47, v164 dst_sel:DWORD dst_unused:UNUSED_PAD src0_sel:WORD_1
	v_cvt_f32_f16_e32 v48, v164
	v_cvt_f32_f16_sdwa v49, v165 dst_sel:DWORD dst_unused:UNUSED_PAD src0_sel:WORD_1
	v_cvt_f32_f16_e32 v50, v165
	s_waitcnt lgkmcnt(0)
	v_sub_f32_e32 v43, v1, v40
	v_sub_f32_e32 v45, v44, v40
	v_sub_f32_e32 v42, v42, v40
	v_sub_f32_e32 v44, v46, v40
	v_pk_mul_f32 v[44:45], v[40:41], v[44:45] op_sel:[1,0]
	v_pk_mul_f32 v[42:43], v[40:41], v[42:43] op_sel:[1,0]
	v_sub_f32_e32 v47, v47, v40
	v_sub_f32_e32 v49, v49, v40
	v_sub_f32_e32 v46, v48, v40
	v_sub_f32_e32 v48, v50, v40
	v_pk_fma_f32 v[42:43], v[94:95], v[42:43], v[98:99]
	v_pk_fma_f32 v[44:45], v[96:97], v[44:45], v[100:101]
	v_pk_mul_f32 v[48:49], v[40:41], v[48:49] op_sel:[1,0]
	v_pk_mul_f32 v[46:47], v[40:41], v[46:47] op_sel:[1,0]
	v_pk_fma_f32 v[48:49], v[88:89], v[48:49], v[92:93]
	v_pk_fma_f32 v[46:47], v[86:87], v[46:47], v[90:91]
	v_pk_fma_f32 v[36:37], v[44:45], s[18:19], v[36:37] op_sel_hi:[1,0,1]
	v_pk_fma_f32 v[34:35], v[42:43], s[18:19], v[34:35] op_sel_hi:[1,0,1]
	v_pk_fma_f32 v[42:43], v[48:49], s[18:19], v[32:33] op_sel_hi:[1,0,1]
	v_pk_fma_f32 v[32:33], v[46:47], s[18:19], v[30:31] op_sel_hi:[1,0,1]
	v_pk_mov_b32 v[30:31], v[34:35], v[36:37] op_sel:[1,0]
	v_mov_b32_e32 v44, v34
	v_mov_b32_e32 v45, v37
	v_pk_add_f32 v[44:45], v[30:31], v[44:45]
	v_pk_mul_f32 v[30:31], v[36:37], v[36:37]
	v_pk_mul_f32 v[48:49], v[34:35], v[34:35]
	v_lshlrev_b64 v[38:39], 10, v[128:129]
	v_pk_mov_b32 v[50:51], v[48:49], v[30:31] op_sel:[1,0]
	v_mov_b32_e32 v49, v31
	v_pk_add_f32 v[30:31], v[50:51], v[48:49]
	v_lshl_add_u64 v[38:39], v[38:39], 1, v[200:201]
	v_pk_add_f32 v[48:49], v[30:31], v[30:31] op_sel_hi:[0,1]
	v_mul_f32_e32 v30, v32, v32
	v_add_f32_e32 v46, v32, v33
	v_pk_fma_f32 v[50:51], v[32:33], v[32:33], v[30:31] op_sel_hi:[1,1,0]
	v_cvt_pk_f16_f32 v30, v34, v35
	v_cvt_pk_f16_f32 v31, v36, v37
	v_cvt_pk_f16_f32 v32, v32, v33
	v_cvt_pk_f16_f32 v33, v42, v43
	global_store_dwordx4 v[38:39], v[30:33], off
	s_waitcnt vmcnt(7)
	v_cvt_f32_f16_e32 v34, v167
	v_cvt_f32_f16_sdwa v35, v168 dst_sel:DWORD dst_unused:UNUSED_PAD src0_sel:WORD_1
	v_cvt_f32_f16_sdwa v30, v166 dst_sel:DWORD dst_unused:UNUSED_PAD src0_sel:WORD_1
	v_cvt_f32_f16_e32 v32, v166
	v_cvt_f32_f16_sdwa v33, v167 dst_sel:DWORD dst_unused:UNUSED_PAD src0_sel:WORD_1
	v_cvt_f32_f16_e32 v36, v168
	v_cvt_f32_f16_sdwa v37, v169 dst_sel:DWORD dst_unused:UNUSED_PAD src0_sel:WORD_1
	v_cvt_f32_f16_e32 v47, v169
	v_sub_f32_e32 v31, v30, v40
	v_sub_f32_e32 v33, v33, v40
	v_sub_f32_e32 v30, v32, v40
	v_sub_f32_e32 v32, v34, v40
	v_pk_mul_f32 v[32:33], v[40:41], v[32:33] op_sel:[1,0]
	v_pk_mul_f32 v[30:31], v[40:41], v[30:31] op_sel:[1,0]
	v_sub_f32_e32 v35, v35, v40
	v_sub_f32_e32 v37, v37, v40
	v_sub_f32_e32 v34, v36, v40
	v_sub_f32_e32 v36, v47, v40
	v_pk_fma_f32 v[30:31], v[78:79], v[30:31], v[82:83]
	v_pk_fma_f32 v[32:33], v[80:81], v[32:33], v[84:85]
	v_pk_mul_f32 v[36:37], v[40:41], v[36:37] op_sel:[1,0]
	v_pk_mul_f32 v[34:35], v[40:41], v[34:35] op_sel:[1,0]
	v_pk_fma_f32 v[36:37], v[68:69], v[36:37], v[76:77]
	v_pk_fma_f32 v[34:35], v[66:67], v[34:35], v[74:75]
	v_pk_fma_f32 v[28:29], v[32:33], s[18:19], v[28:29] op_sel_hi:[1,0,1]
	v_pk_fma_f32 v[26:27], v[30:31], s[18:19], v[26:27] op_sel_hi:[1,0,1]
	v_pk_fma_f32 v[30:31], v[36:37], s[18:19], v[24:25] op_sel_hi:[1,0,1]
	v_pk_fma_f32 v[24:25], v[34:35], s[18:19], v[22:23] op_sel_hi:[1,0,1]
	v_pk_mov_b32 v[22:23], v[26:27], v[28:29] op_sel:[1,0]
	v_mov_b32_e32 v32, v26
	v_mov_b32_e32 v33, v29
	v_pk_add_f32 v[32:33], v[22:23], v[32:33]
	v_mul_f32_e32 v22, v26, v26
	v_pk_fma_f32 v[34:35], v[26:27], v[26:27], v[22:23] op_sel_hi:[1,1,0]
	v_mul_f32_e32 v22, v28, v28
	v_pk_fma_f32 v[36:37], v[28:29], v[28:29], v[22:23] op_sel_hi:[1,1,0]
	v_mul_f32_e32 v22, v30, v30
	v_add_f32_e32 v52, v24, v25
	v_mul_f32_e32 v47, v24, v24
	v_mul_f32_e32 v54, v25, v25
	v_pk_fma_f32 v[40:41], v[30:31], v[30:31], v[22:23] op_sel_hi:[1,1,0]
	v_cvt_pk_f16_f32 v22, v26, v27
	v_cvt_pk_f16_f32 v23, v28, v29
	v_cvt_pk_f16_f32 v24, v24, v25
	v_cvt_pk_f16_f32 v25, v30, v31
	v_mul_f32_e32 v1, v43, v43
	global_store_dwordx4 v[38:39], v[22:25], off offset:256
	v_mul_f32_e32 v53, v42, v42
	v_mov_b32_e32 v50, v30
	v_pk_add_f32 v[22:23], v[32:33], v[32:33] op_sel:[0,1] op_sel_hi:[1,0]
	v_mov_b32_e32 v48, v31
	v_mov_b32_e32 v23, v1
	v_pk_add_f32 v[26:27], v[44:45], v[44:45] op_sel:[0,1] op_sel_hi:[1,0]
	v_pk_add_f32 v[22:23], v[52:53], v[22:23]
	v_pk_add_f32 v[24:25], v[50:51], v[48:49]
	v_mov_b32_e32 v34, v42
	v_mov_b32_e32 v36, v43
	v_mov_b32_e32 v27, v54
	v_pk_add_f32 v[22:23], v[22:23], v[24:25]
	v_pk_add_f32 v[24:25], v[34:35], v[36:37]
	v_pk_add_f32 v[26:27], v[46:47], v[26:27]
	v_mov_b32_e32 v1, v41
	v_pk_add_f32 v[24:25], v[26:27], v[24:25]
	s_nop 0
	v_pk_add_f32 v[24:25], v[24:25], v[0:1]
	s_nop 0
	v_pk_add_f32 v[22:23], v[22:23], v[24:25]
	ds_bpermute_b32 v24, v228, v22
	ds_bpermute_b32 v25, v228, v23
	s_waitcnt lgkmcnt(0)
	v_pk_add_f32 v[22:23], v[22:23], v[24:25]
	ds_bpermute_b32 v24, v227, v22
	ds_bpermute_b32 v25, v227, v23
	s_and_saveexec_b64 s[22:23], s[36:37]
	s_cbranch_execz .LBB0_801
	s_waitcnt lgkmcnt(0)
	v_pk_add_f32 v[22:23], v[22:23], v[24:25]
	v_lshlrev_b64 v[24:25], 7, v[128:129]
	v_lshl_add_u64 v[24:25], s[0:1], 0, v[24:25]
	v_lshl_add_u64 v[24:25], s[16:17], 3, v[24:25]
	s_lshl_b32 s58, s72, 3
	v_lshl_add_u64 v[24:25], v[24:25], 0, s[58:59]
	global_store_dwordx2 v[24:25], v[22:23], off
; #define PG8_LAS __attribute__((address_space(3)))
;     __device__ __forceinline__ void operator()(const f32x4 (&acc)[2][2][4][2], const Unit& u, int ui, int wr, int wc, int fr, int fq) const {
;     ...
;                 for (int bj = 0; bj < 2; ++bj) rr[m][bj] = *(const bf16x8*)(R + (size_t)(row0 + ai * HALF + m * 16) * ldc + col0 + bj * HALF);
;             __builtin_amdgcn_sched_barrier(0); }
; #pragma unroll
;             for (int m = 0; m < 4; ++m) { const int row = row0 + ai * HALF + m * 16; const size_t off = (size_t)row * ldc + col0;
;                 float mu = 0.f, rs = 1.f; if (FOLD) { const f32x2_t ms = ((const PG8_LAS f32x2_t*)tb)[pslot + ai * HALF + wr * 64 + m * 16 + fr]; mu = ms.x; rs = ms.y; }
;                 float ssum = 0.f, ssq = 0.f;
; #pragma unroll
;                 for (int bj = 0; bj < 2; ++bj) { f32x4 v0 = acc[ai][bj][m][0], v1 = acc[ai][bj][m][1];
;                     if (FOLD && MODE != 2) { v0 = (v0 - mu * cv[bj][0]) * rs + bv[bj][0]; v1 = (v1 - mu * cv[bj][1]) * rs + bv[bj][1]; }
;                     if (MODE == 0) { v0 = v0 * sc; v1 = v1 * sc; }
;                     if (MODE == 1) { v0 = __builtin_elementwise_max(v0, (f32x4){0.f, 0.f, 0.f, 0.f}); v1 = __builtin_elementwise_max(v1, (f32x4){0.f, 0.f, 0.f, 0.f}); v0 = v0 * v0; v1 = v1 * v1; }
;                     if (MODE == 2) { const bf16x8 r = rr[m][bj];
;                         f32x4 h0 = (f32x4){(float)r[0], (float)r[1], (float)r[2], (float)r[3]}, h1 = (f32x4){(float)r[4], (float)r[5], (float)r[6], (float)r[7]};
;                         if (FOLD) { h0 = (h0 - mu) * rs * cv[bj][0] + bv[bj][0]; h1 = (h1 - mu) * rs * cv[bj][1] + bv[bj][1]; }
;                         v0 = v0 + alpha * h0; v1 = v1 + alpha * h1;
;                         ssum += (v0[0] + v0[1]) + (v0[2] + v0[3]) + (v1[0] + v1[1]) + (v1[2] + v1[3]);
;                         ssq += (v0[0] * v0[0] + v0[1] * v0[1]) + (v0[2] * v0[2] + v0[3] * v0[3]) + (v1[0] * v1[0] + v1[1] * v1[1]) + (v1[2] * v1[2] + v1[3] * v1[3]); }
;                     u32x4 w; w.x = pk2h(v0[0], v0[1]); w.y = pk2h(v0[2], v0[3]); w.z = pk2h(v1[0], v1[1]); w.w = pk2h(v1[2], v1[3]);
;                     if (MODE == 0 && hm) { const int cc = col0 + bj * HALF; *(u32x4*)(base + ((size_t)(row >> 11) * 16 + (cc >> 6)) * 131072 + (size_t)(row & 2047) * 64 + (cc & 63)) = w; }
;                     else *(u32x4*)(base + off + bj * HALF) = w; }
.LBB0_801:
	s_or_b64 exec, exec, s[22:23]
	s_waitcnt lgkmcnt(0)
	ds_read_b64 v[24:25], v229 offset:1408
	s_waitcnt vmcnt(7)
	v_cvt_f32_f16_sdwa v1, v154 dst_sel:DWORD dst_unused:UNUSED_PAD src0_sel:WORD_1
	v_cvt_f32_f16_e32 v26, v154
	v_cvt_f32_f16_sdwa v28, v155 dst_sel:DWORD dst_unused:UNUSED_PAD src0_sel:WORD_1
	v_cvt_f32_f16_e32 v30, v155
	v_cvt_f32_f16_sdwa v31, v156 dst_sel:DWORD dst_unused:UNUSED_PAD src0_sel:WORD_1
	v_cvt_f32_f16_e32 v32, v156
	v_cvt_f32_f16_sdwa v33, v157 dst_sel:DWORD dst_unused:UNUSED_PAD src0_sel:WORD_1
	v_cvt_f32_f16_e32 v34, v157
	s_waitcnt lgkmcnt(0)
	v_sub_f32_e32 v27, v1, v24
	v_sub_f32_e32 v29, v28, v24
	v_sub_f32_e32 v26, v26, v24
	v_sub_f32_e32 v28, v30, v24
	v_pk_mul_f32 v[28:29], v[24:25], v[28:29] op_sel:[1,0]
	v_pk_mul_f32 v[26:27], v[24:25], v[26:27] op_sel:[1,0]
	v_sub_f32_e32 v31, v31, v24
	v_sub_f32_e32 v33, v33, v24
	v_sub_f32_e32 v30, v32, v24
	v_sub_f32_e32 v32, v34, v24
	v_pk_fma_f32 v[26:27], v[94:95], v[26:27], v[98:99]
	v_pk_fma_f32 v[28:29], v[96:97], v[28:29], v[100:101]
	v_pk_mul_f32 v[32:33], v[24:25], v[32:33] op_sel:[1,0]
	v_pk_mul_f32 v[30:31], v[24:25], v[30:31] op_sel:[1,0]
	v_pk_fma_f32 v[32:33], v[88:89], v[32:33], v[92:93]
	v_pk_fma_f32 v[30:31], v[86:87], v[30:31], v[90:91]
	v_pk_fma_f32 v[20:21], v[28:29], s[18:19], v[20:21] op_sel_hi:[1,0,1]
	v_pk_fma_f32 v[18:19], v[26:27], s[18:19], v[18:19] op_sel_hi:[1,0,1]
	v_pk_fma_f32 v[26:27], v[32:33], s[18:19], v[12:13] op_sel_hi:[1,0,1]
	v_pk_fma_f32 v[12:13], v[30:31], s[18:19], v[10:11] op_sel_hi:[1,0,1]
	v_pk_mov_b32 v[10:11], v[18:19], v[20:21] op_sel:[1,0]
	v_mov_b32_e32 v28, v18
	v_mov_b32_e32 v29, v21
	v_pk_add_f32 v[28:29], v[10:11], v[28:29]
	v_pk_mul_f32 v[10:11], v[20:21], v[20:21]
	v_pk_mul_f32 v[32:33], v[18:19], v[18:19]
	s_waitcnt vmcnt(6)
	v_cvt_f32_f16_e32 v31, v103
	v_pk_mov_b32 v[34:35], v[32:33], v[10:11] op_sel:[1,0]
	v_mov_b32_e32 v33, v11
	v_pk_add_f32 v[10:11], v[34:35], v[32:33]
	v_cvt_f32_f16_sdwa v36, v105 dst_sel:DWORD dst_unused:UNUSED_PAD src0_sel:WORD_1
	v_pk_add_f32 v[32:33], v[10:11], v[10:11] op_sel_hi:[0,1]
	v_mul_f32_e32 v10, v12, v12
	v_pk_fma_f32 v[34:35], v[12:13], v[12:13], v[10:11] op_sel_hi:[1,1,0]
	v_cvt_pk_f16_f32 v10, v18, v19
	v_cvt_pk_f16_f32 v11, v20, v21
	v_cvt_f32_f16_sdwa v18, v102 dst_sel:DWORD dst_unused:UNUSED_PAD src0_sel:WORD_1
	v_cvt_f32_f16_e32 v20, v102
	v_cvt_f32_f16_sdwa v21, v103 dst_sel:DWORD dst_unused:UNUSED_PAD src0_sel:WORD_1
	v_cvt_f32_f16_sdwa v32, v104 dst_sel:DWORD dst_unused:UNUSED_PAD src0_sel:WORD_1
	v_cvt_f32_f16_e32 v34, v104
	v_cvt_f32_f16_e32 v40, v105
	v_sub_f32_e32 v19, v18, v24
	v_sub_f32_e32 v21, v21, v24
	v_sub_f32_e32 v18, v20, v24
	v_sub_f32_e32 v20, v31, v24
	v_pk_mul_f32 v[20:21], v[24:25], v[20:21] op_sel:[1,0]
	v_pk_mul_f32 v[18:19], v[24:25], v[18:19] op_sel:[1,0]
	v_sub_f32_e32 v39, v32, v24
	v_sub_f32_e32 v41, v36, v24
	v_sub_f32_e32 v38, v34, v24
	v_sub_f32_e32 v40, v40, v24
	v_pk_fma_f32 v[18:19], v[78:79], v[18:19], v[82:83]
	v_pk_fma_f32 v[20:21], v[80:81], v[20:21], v[84:85]
	v_pk_mul_f32 v[40:41], v[24:25], v[40:41] op_sel:[1,0]
	v_pk_mul_f32 v[24:25], v[24:25], v[38:39] op_sel:[1,0]
	v_pk_fma_f32 v[38:39], v[68:69], v[40:41], v[76:77]
	v_pk_fma_f32 v[24:25], v[66:67], v[24:25], v[74:75]
	v_pk_fma_f32 v[8:9], v[20:21], s[18:19], v[8:9] op_sel_hi:[1,0,1]
	v_pk_fma_f32 v[6:7], v[18:19], s[18:19], v[6:7] op_sel_hi:[1,0,1]
	v_pk_fma_f32 v[18:19], v[38:39], s[18:19], v[4:5] op_sel_hi:[1,0,1]
	v_pk_fma_f32 v[20:21], v[24:25], s[18:19], v[2:3] op_sel_hi:[1,0,1]
	v_pk_mov_b32 v[2:3], v[6:7], v[8:9] op_sel:[1,0]
	v_mov_b32_e32 v4, v6
	v_mov_b32_e32 v5, v9
	v_pk_add_f32 v[2:3], v[2:3], v[4:5]
	v_mul_f32_e32 v4, v6, v6
	v_pk_fma_f32 v[4:5], v[6:7], v[6:7], v[4:5] op_sel_hi:[1,1,0]
	v_mul_f32_e32 v40, v21, v21
	v_mul_f32_e32 v4, v8, v8
	v_pk_fma_f32 v[24:25], v[8:9], v[8:9], v[4:5] op_sel_hi:[1,1,0]
	v_mul_f32_e32 v4, v18, v18
	v_pk_fma_f32 v[38:39], v[18:19], v[18:19], v[4:5] op_sel_hi:[1,1,0]
	v_mov_b32_e32 v4, v26
	v_mov_b32_e32 v24, v27
	v_pk_add_f32 v[4:5], v[4:5], v[24:25]
	v_pk_add_f32 v[24:25], v[28:29], v[28:29] op_sel:[0,1] op_sel_hi:[1,0]
	v_add_f32_e32 v30, v12, v13
	v_mul_f32_e32 v1, v27, v27
	v_mul_f32_e32 v31, v20, v20
	v_pk_add_f32 v[2:3], v[2:3], v[2:3] op_sel:[0,1] op_sel_hi:[1,0]
	v_mov_b32_e32 v25, v40
	v_mul_f32_e32 v37, v26, v26
	v_add_f32_e32 v36, v20, v21
	v_mov_b32_e32 v3, v1
	v_mov_b32_e32 v34, v18
	v_mov_b32_e32 v32, v19
	v_pk_add_f32 v[24:25], v[30:31], v[24:25]
	v_pk_add_f32 v[2:3], v[36:37], v[2:3]
	v_pk_add_f32 v[32:33], v[34:35], v[32:33]
	v_pk_add_f32 v[4:5], v[24:25], v[4:5]
	v_mov_b32_e32 v1, v39
	v_pk_add_f32 v[2:3], v[2:3], v[32:33]
	v_pk_add_f32 v[4:5], v[4:5], v[0:1]
	v_lshlrev_b64 v[22:23], 10, v[126:127]
	v_pk_add_f32 v[2:3], v[2:3], v[4:5]
	ds_bpermute_b32 v4, v228, v2
	ds_bpermute_b32 v5, v228, v3
	v_lshl_add_u64 v[22:23], v[22:23], 1, v[200:201]
	v_cvt_pk_f16_f32 v12, v12, v13
	v_cvt_pk_f16_f32 v13, v26, v27
	v_cvt_pk_f16_f32 v6, v6, v7
	s_waitcnt lgkmcnt(0)
	v_pk_add_f32 v[2:3], v[2:3], v[4:5]
	ds_bpermute_b32 v4, v227, v2
	ds_bpermute_b32 v5, v227, v3
	v_cvt_pk_f16_f32 v7, v8, v9
	v_cvt_pk_f16_f32 v8, v20, v21
	v_cvt_pk_f16_f32 v9, v18, v19
	global_store_dwordx4 v[22:23], v[10:13], off
	global_store_dwordx4 v[22:23], v[6:9], off offset:256
	s_and_saveexec_b64 s[22:23], s[36:37]
	s_cbranch_execz .LBB0_803
	s_waitcnt lgkmcnt(0)
	v_pk_add_f32 v[2:3], v[2:3], v[4:5]
	v_lshlrev_b64 v[4:5], 7, v[126:127]
	v_lshl_add_u64 v[4:5], s[0:1], 0, v[4:5]
	v_lshl_add_u64 v[4:5], s[16:17], 3, v[4:5]
	s_lshl_b32 s58, s72, 3
	v_lshl_add_u64 v[4:5], v[4:5], 0, s[58:59]
	global_store_dwordx2 v[4:5], v[2:3], off

; #define PG8_LAS __attribute__((address_space(3)))
;     __device__ __forceinline__ void operator()(const f32x4 (&acc)[2][2][4][2], const Unit& u, int ui, int wr, int wc, int fr, int fq) const {
;     ...
;                 for (int bj = 0; bj < 2; ++bj) rr[m][bj] = *(const bf16x8*)(R + (size_t)(row0 + ai * HALF + m * 16) * ldc + col0 + bj * HALF);
;             __builtin_amdgcn_sched_barrier(0); }
; #pragma unroll
;             for (int m = 0; m < 4; ++m) { const int row = row0 + ai * HALF + m * 16; const size_t off = (size_t)row * ldc + col0;
;                 float mu = 0.f, rs = 1.f; if (FOLD) { const f32x2_t ms = ((const PG8_LAS f32x2_t*)tb)[pslot + ai * HALF + wr * 64 + m * 16 + fr]; mu = ms.x; rs = ms.y; }
;                 float ssum = 0.f, ssq = 0.f;
; #pragma unroll
;                 for (int bj = 0; bj < 2; ++bj) { f32x4 v0 = acc[ai][bj][m][0], v1 = acc[ai][bj][m][1];
;                     if (FOLD && MODE != 2) { v0 = (v0 - mu * cv[bj][0]) * rs + bv[bj][0]; v1 = (v1 - mu * cv[bj][1]) * rs + bv[bj][1]; }
;                     if (MODE == 0) { v0 = v0 * sc; v1 = v1 * sc; }
;                     if (MODE == 1) { v0 = __builtin_elementwise_max(v0, (f32x4){0.f, 0.f, 0.f, 0.f}); v1 = __builtin_elementwise_max(v1, (f32x4){0.f, 0.f, 0.f, 0.f}); v0 = v0 * v0; v1 = v1 * v1; }
;                     if (MODE == 2) { const bf16x8 r = rr[m][bj];
;                         f32x4 h0 = (f32x4){(float)r[0], (float)r[1], (float)r[2], (float)r[3]}, h1 = (f32x4){(float)r[4], (float)r[5], (float)r[6], (float)r[7]};
;                         if (FOLD) { h0 = (h0 - mu) * rs * cv[bj][0] + bv[bj][0]; h1 = (h1 - mu) * rs * cv[bj][1] + bv[bj][1]; }
;                         v0 = v0 + alpha * h0; v1 = v1 + alpha * h1;
;                         ssum += (v0[0] + v0[1]) + (v0[2] + v0[3]) + (v1[0] + v1[1]) + (v1[2] + v1[3]);
;                         ssq += (v0[0] * v0[0] + v0[1] * v0[1]) + (v0[2] * v0[2] + v0[3] * v0[3]) + (v1[0] * v1[0] + v1[1] * v1[1]) + (v1[2] * v1[2] + v1[3] * v1[3]); }
;                     u32x4 w; w.x = pk2h(v0[0], v0[1]); w.y = pk2h(v0[2], v0[3]); w.z = pk2h(v1[0], v1[1]); w.w = pk2h(v1[2], v1[3]);
;                     if (MODE == 0 && hm) { const int cc = col0 + bj * HALF; *(u32x4*)(base + ((size_t)(row >> 11) * 16 + (cc >> 6)) * 131072 + (size_t)(row & 2047) * 64 + (cc & 63)) = w; }
;                     else *(u32x4*)(base + off + bj * HALF) = w; }
.LBB0_1141:
	s_or_b64 exec, exec, s[22:23]
	v_add_u32_e32 v156, 0x80, v202
	v_ashrrev_i32_e32 v157, 31, v156
	v_lshlrev_b64 v[156:157], 11, v[156:157]
	v_lshl_add_u64 v[156:157], v[204:205], 0, v[156:157]
	global_load_dwordx4 v[208:211], v[156:157], off
	global_load_dwordx4 v[212:215], v[156:157], off offset:256
	v_add_u32_e32 v156, 0x90, v202
	v_ashrrev_i32_e32 v157, 31, v156
	v_lshlrev_b64 v[156:157], 11, v[156:157]
	v_lshl_add_u64 v[156:157], v[204:205], 0, v[156:157]
	global_load_dwordx4 v[182:185], v[156:157], off
	global_load_dwordx4 v[186:189], v[156:157], off offset:256
	v_add_u32_e32 v156, 0xa0, v202
	v_ashrrev_i32_e32 v157, 31, v156
	v_lshlrev_b64 v[156:157], 11, v[156:157]
	v_lshl_add_u64 v[156:157], v[204:205], 0, v[156:157]
	global_load_dwordx4 v[162:165], v[156:157], off
	global_load_dwordx4 v[166:169], v[156:157], off offset:256
	v_add_u32_e32 v156, 0xb0, v202
	v_ashrrev_i32_e32 v157, 31, v156
	v_lshlrev_b64 v[156:157], 11, v[156:157]
	v_lshl_add_u64 v[156:157], v[204:205], 0, v[156:157]
	global_load_dwordx4 v[154:157], v[156:157], off
	s_waitcnt lgkmcnt(0)
	ds_read_b64 v[136:137], v228 offset:256
	v_cvt_f32_f16_sdwa v1, v178 dst_sel:DWORD dst_unused:UNUSED_PAD src0_sel:WORD_1
	v_cvt_f32_f16_e32 v138, v178
	v_cvt_f32_f16_sdwa v140, v179 dst_sel:DWORD dst_unused:UNUSED_PAD src0_sel:WORD_1
	v_cvt_f32_f16_e32 v142, v179
	v_cvt_f32_f16_sdwa v143, v180 dst_sel:DWORD dst_unused:UNUSED_PAD src0_sel:WORD_1
	v_cvt_f32_f16_e32 v144, v180
	v_cvt_f32_f16_sdwa v145, v181 dst_sel:DWORD dst_unused:UNUSED_PAD src0_sel:WORD_1
	v_cvt_f32_f16_e32 v146, v181
	s_waitcnt lgkmcnt(0)
	v_sub_f32_e32 v139, v1, v136
	v_sub_f32_e32 v141, v140, v136
	v_sub_f32_e32 v138, v138, v136
	v_sub_f32_e32 v140, v142, v136
	v_pk_mul_f32 v[140:141], v[136:137], v[140:141] op_sel:[1,0]
	v_pk_mul_f32 v[138:139], v[136:137], v[138:139] op_sel:[1,0]
	v_sub_f32_e32 v143, v143, v136
	v_sub_f32_e32 v145, v145, v136
	v_sub_f32_e32 v142, v144, v136
	v_sub_f32_e32 v144, v146, v136
	v_pk_fma_f32 v[138:139], v[94:95], v[138:139], v[98:99]
	v_pk_fma_f32 v[140:141], v[96:97], v[140:141], v[100:101]
	v_pk_mul_f32 v[144:145], v[136:137], v[144:145] op_sel:[1,0]
	v_pk_mul_f32 v[142:143], v[136:137], v[142:143] op_sel:[1,0]
	v_pk_fma_f32 v[144:145], v[88:89], v[144:145], v[92:93]
	v_pk_fma_f32 v[142:143], v[86:87], v[142:143], v[90:91]
	v_pk_fma_f32 v[132:133], v[140:141], s[18:19], v[132:133] op_sel_hi:[1,0,1]
	v_pk_fma_f32 v[130:131], v[138:139], s[18:19], v[130:131] op_sel_hi:[1,0,1]
	v_pk_fma_f32 v[138:139], v[144:145], s[18:19], v[128:129] op_sel_hi:[1,0,1]
	v_pk_fma_f32 v[128:129], v[142:143], s[18:19], v[126:127] op_sel_hi:[1,0,1]
	v_pk_mov_b32 v[126:127], v[130:131], v[132:133] op_sel:[1,0]
	v_mov_b32_e32 v140, v130
	v_mov_b32_e32 v141, v133
	v_pk_add_f32 v[140:141], v[126:127], v[140:141]
	v_pk_mul_f32 v[126:127], v[132:133], v[132:133]
	v_pk_mul_f32 v[144:145], v[130:131], v[130:131]
	v_lshlrev_b64 v[134:135], 10, v[218:219]
	v_pk_mov_b32 v[146:147], v[144:145], v[126:127] op_sel:[1,0]
	v_mov_b32_e32 v145, v127
	v_pk_add_f32 v[126:127], v[146:147], v[144:145]
	v_lshl_add_u64 v[134:135], v[134:135], 1, v[200:201]
	v_pk_add_f32 v[144:145], v[126:127], v[126:127] op_sel_hi:[0,1]
	v_mul_f32_e32 v126, v128, v128
	v_add_f32_e32 v142, v128, v129
	v_pk_fma_f32 v[146:147], v[128:129], v[128:129], v[126:127] op_sel_hi:[1,1,0]
	v_cvt_pk_f16_f32 v126, v130, v131
	v_cvt_pk_f16_f32 v127, v132, v133
	v_cvt_pk_f16_f32 v128, v128, v129
	v_cvt_pk_f16_f32 v129, v138, v139
	global_store_dwordx4 v[134:135], v[126:129], off
	v_cvt_f32_f16_e32 v130, v175
	v_cvt_f32_f16_sdwa v131, v176 dst_sel:DWORD dst_unused:UNUSED_PAD src0_sel:WORD_1
	v_cvt_f32_f16_sdwa v126, v174 dst_sel:DWORD dst_unused:UNUSED_PAD src0_sel:WORD_1
	v_cvt_f32_f16_e32 v128, v174
	v_cvt_f32_f16_sdwa v129, v175 dst_sel:DWORD dst_unused:UNUSED_PAD src0_sel:WORD_1
	v_cvt_f32_f16_e32 v132, v176
	v_cvt_f32_f16_sdwa v133, v177 dst_sel:DWORD dst_unused:UNUSED_PAD src0_sel:WORD_1
	v_cvt_f32_f16_e32 v143, v177
	v_sub_f32_e32 v127, v126, v136
	v_sub_f32_e32 v129, v129, v136
	v_sub_f32_e32 v126, v128, v136
	v_sub_f32_e32 v128, v130, v136
	v_pk_mul_f32 v[128:129], v[136:137], v[128:129] op_sel:[1,0]
	v_pk_mul_f32 v[126:127], v[136:137], v[126:127] op_sel:[1,0]
	v_sub_f32_e32 v131, v131, v136
	v_sub_f32_e32 v133, v133, v136
	v_sub_f32_e32 v130, v132, v136
	v_sub_f32_e32 v132, v143, v136
	v_pk_fma_f32 v[126:127], v[78:79], v[126:127], v[82:83]
	v_pk_fma_f32 v[128:129], v[80:81], v[128:129], v[84:85]
	v_pk_mul_f32 v[132:133], v[136:137], v[132:133] op_sel:[1,0]
	v_pk_mul_f32 v[130:131], v[136:137], v[130:131] op_sel:[1,0]
	v_pk_fma_f32 v[132:133], v[68:69], v[132:133], v[72:73]
	v_pk_fma_f32 v[130:131], v[66:67], v[130:131], v[70:71]
	v_pk_fma_f32 v[124:125], v[128:129], s[18:19], v[124:125] op_sel_hi:[1,0,1]
	v_pk_fma_f32 v[122:123], v[126:127], s[18:19], v[122:123] op_sel_hi:[1,0,1]
	v_pk_fma_f32 v[126:127], v[132:133], s[18:19], v[120:121] op_sel_hi:[1,0,1]
	v_pk_fma_f32 v[120:121], v[130:131], s[18:19], v[118:119] op_sel_hi:[1,0,1]
	v_pk_mov_b32 v[118:119], v[122:123], v[124:125] op_sel:[1,0]
	v_mov_b32_e32 v128, v122
	v_mov_b32_e32 v129, v125
	v_pk_add_f32 v[128:129], v[118:119], v[128:129]
	v_mul_f32_e32 v118, v122, v122
	v_pk_fma_f32 v[130:131], v[122:123], v[122:123], v[118:119] op_sel_hi:[1,1,0]
	v_mul_f32_e32 v118, v124, v124
	v_pk_fma_f32 v[132:133], v[124:125], v[124:125], v[118:119] op_sel_hi:[1,1,0]
	v_mul_f32_e32 v118, v126, v126
	v_add_f32_e32 v148, v120, v121
	v_mul_f32_e32 v143, v120, v120
	v_mul_f32_e32 v150, v121, v121
	v_pk_fma_f32 v[136:137], v[126:127], v[126:127], v[118:119] op_sel_hi:[1,1,0]
	v_cvt_pk_f16_f32 v118, v122, v123
	v_cvt_pk_f16_f32 v119, v124, v125
	v_cvt_pk_f16_f32 v120, v120, v121
	v_cvt_pk_f16_f32 v121, v126, v127
	v_mul_f32_e32 v1, v139, v139
	global_store_dwordx4 v[134:135], v[118:121], off offset:256
	v_mul_f32_e32 v149, v138, v138
	v_mov_b32_e32 v146, v126
	v_pk_add_f32 v[118:119], v[128:129], v[128:129] op_sel:[0,1] op_sel_hi:[1,0]
	v_mov_b32_e32 v144, v127
	v_mov_b32_e32 v119, v1
	v_pk_add_f32 v[122:123], v[140:141], v[140:141] op_sel:[0,1] op_sel_hi:[1,0]
	v_pk_add_f32 v[118:119], v[148:149], v[118:119]
	v_pk_add_f32 v[120:121], v[146:147], v[144:145]
	v_mov_b32_e32 v130, v138
	v_mov_b32_e32 v132, v139
	v_mov_b32_e32 v123, v150
	v_pk_add_f32 v[118:119], v[118:119], v[120:121]
	v_pk_add_f32 v[120:121], v[130:131], v[132:133]
	v_pk_add_f32 v[122:123], v[142:143], v[122:123]
	v_mov_b32_e32 v1, v137
	v_pk_add_f32 v[120:121], v[122:123], v[120:121]
	s_nop 0
	v_pk_add_f32 v[120:121], v[120:121], v[0:1]
	s_nop 0
	v_pk_add_f32 v[118:119], v[118:119], v[120:121]
	ds_bpermute_b32 v120, v227, v118
	ds_bpermute_b32 v121, v227, v119
	s_waitcnt lgkmcnt(0)
	v_pk_add_f32 v[118:119], v[118:119], v[120:121]
	ds_bpermute_b32 v120, v226, v118
	ds_bpermute_b32 v121, v226, v119
	s_and_saveexec_b64 s[22:23], s[36:37]
	v_readlane_b32 s54, v255, 25
	v_readlane_b32 s55, v255, 26
	s_cbranch_execz .LBB0_1143
;     __device__ __forceinline__ void operator()(const f32x4 (&acc)[2][2][4][2], const Unit& u, int ui, int wr, int wc, int fr, int fq) const {
;     ...
;                 if (MODE == 2) { ssum += __shfl_xor(ssum, 16); ssq += __shfl_xor(ssq, 16); ssum += __shfl_xor(ssum, 32); ssq += __shfl_xor(ssq, 32);
;                     if (fq == 0) part[(size_t)(row0 + ai * HALF + m * 16) * 16 + u.pn * 4 + wc] = (f32x2_t){ssum, ssq}; } }
	s_waitcnt lgkmcnt(0)
	v_pk_add_f32 v[118:119], v[118:119], v[120:121]
	v_lshlrev_b64 v[120:121], 7, v[218:219]
	v_lshl_add_u64 v[120:121], s[44:45], 0, v[120:121]
	v_lshl_add_u64 v[120:121], vcc, 3, v[120:121]
	s_lshl_b32 s58, s71, 3
	v_lshl_add_u64 v[120:121], v[120:121], 0, s[58:59]
	global_store_dwordx2 v[120:121], v[118:119], off

; #define PG8_LAS __attribute__((address_space(3)))
;     __device__ __forceinline__ void operator()(const f32x4 (&acc)[2][2][4][2], const Unit& u, int ui, int wr, int wc, int fr, int fq) const {
;     ...
;                 for (int bj = 0; bj < 2; ++bj) rr[m][bj] = *(const bf16x8*)(R + (size_t)(row0 + ai * HALF + m * 16) * ldc + col0 + bj * HALF);
;             __builtin_amdgcn_sched_barrier(0); }
; #pragma unroll
;             for (int m = 0; m < 4; ++m) { const int row = row0 + ai * HALF + m * 16; const size_t off = (size_t)row * ldc + col0;
;                 float mu = 0.f, rs = 1.f; if (FOLD) { const f32x2_t ms = ((const PG8_LAS f32x2_t*)tb)[pslot + ai * HALF + wr * 64 + m * 16 + fr]; mu = ms.x; rs = ms.y; }
;                 float ssum = 0.f, ssq = 0.f;
; #pragma unroll
;                 for (int bj = 0; bj < 2; ++bj) { f32x4 v0 = acc[ai][bj][m][0], v1 = acc[ai][bj][m][1];
;                     if (FOLD && MODE != 2) { v0 = (v0 - mu * cv[bj][0]) * rs + bv[bj][0]; v1 = (v1 - mu * cv[bj][1]) * rs + bv[bj][1]; }
;                     if (MODE == 0) { v0 = v0 * sc; v1 = v1 * sc; }
;                     if (MODE == 1) { v0 = __builtin_elementwise_max(v0, (f32x4){0.f, 0.f, 0.f, 0.f}); v1 = __builtin_elementwise_max(v1, (f32x4){0.f, 0.f, 0.f, 0.f}); v0 = v0 * v0; v1 = v1 * v1; }
;                     if (MODE == 2) { const bf16x8 r = rr[m][bj];
;                         f32x4 h0 = (f32x4){(float)r[0], (float)r[1], (float)r[2], (float)r[3]}, h1 = (f32x4){(float)r[4], (float)r[5], (float)r[6], (float)r[7]};
;                         if (FOLD) { h0 = (h0 - mu) * rs * cv[bj][0] + bv[bj][0]; h1 = (h1 - mu) * rs * cv[bj][1] + bv[bj][1]; }
;                         v0 = v0 + alpha * h0; v1 = v1 + alpha * h1;
;                         ssum += (v0[0] + v0[1]) + (v0[2] + v0[3]) + (v1[0] + v1[1]) + (v1[2] + v1[3]);
;                         ssq += (v0[0] * v0[0] + v0[1] * v0[1]) + (v0[2] * v0[2] + v0[3] * v0[3]) + (v1[0] * v1[0] + v1[1] * v1[1]) + (v1[2] * v1[2] + v1[3] * v1[3]); }
;                     u32x4 w; w.x = pk2h(v0[0], v0[1]); w.y = pk2h(v0[2], v0[3]); w.z = pk2h(v1[0], v1[1]); w.w = pk2h(v1[2], v1[3]);
;                     if (MODE == 0 && hm) { const int cc = col0 + bj * HALF; *(u32x4*)(base + ((size_t)(row >> 11) * 16 + (cc >> 6)) * 131072 + (size_t)(row & 2047) * 64 + (cc & 63)) = w; }
;                     else *(u32x4*)(base + off + bj * HALF) = w; }
.LBB0_1145:
	s_or_b64 exec, exec, s[22:23]
	v_add_u32_e32 v132, 0x80, v202
	v_ashrrev_i32_e32 v133, 31, v132
	v_lshlrev_b64 v[142:143], 11, v[132:133]
	v_add_u32_e32 v130, 0x90, v202
	v_lshl_add_u64 v[102:103], v[204:205], 0, v[142:143]
	v_ashrrev_i32_e32 v131, 31, v130
	v_lshlrev_b64 v[102:103], 11, v[130:131]
	v_add_u32_e32 v128, 0xa0, v202
	v_lshl_add_u64 v[102:103], v[204:205], 0, v[102:103]
	v_ashrrev_i32_e32 v129, 31, v128
	v_lshlrev_b64 v[102:103], 11, v[128:129]
	v_add_u32_e32 v126, 0xb0, v202
	v_lshl_add_u64 v[102:103], v[204:205], 0, v[102:103]
	v_ashrrev_i32_e32 v127, 31, v126
	v_lshlrev_b64 v[102:103], 11, v[126:127]
	v_lshl_add_u64 v[102:103], v[204:205], 0, v[102:103]
	s_waitcnt lgkmcnt(0)
	global_load_dwordx4 v[102:105], v[102:103], off offset:256
	ds_read_b64 v[144:145], v228 offset:1024
	s_waitcnt vmcnt(7)
	v_cvt_f32_f16_sdwa v1, v208 dst_sel:DWORD dst_unused:UNUSED_PAD src0_sel:WORD_1
	v_cvt_f32_f16_e32 v134, v208
	v_cvt_f32_f16_sdwa v146, v209 dst_sel:DWORD dst_unused:UNUSED_PAD src0_sel:WORD_1
	v_cvt_f32_f16_e32 v147, v209
	v_cvt_f32_f16_sdwa v148, v210 dst_sel:DWORD dst_unused:UNUSED_PAD src0_sel:WORD_1
	v_cvt_f32_f16_e32 v149, v210
	v_cvt_f32_f16_sdwa v150, v211 dst_sel:DWORD dst_unused:UNUSED_PAD src0_sel:WORD_1
	v_cvt_f32_f16_e32 v151, v211
	s_waitcnt lgkmcnt(0)
	v_sub_f32_e32 v134, v134, v144
	v_sub_f32_e32 v135, v1, v144
	v_sub_f32_e32 v136, v147, v144
	v_sub_f32_e32 v137, v146, v144
	v_pk_mul_f32 v[136:137], v[144:145], v[136:137] op_sel:[1,0]
	v_pk_mul_f32 v[134:135], v[144:145], v[134:135] op_sel:[1,0]
	v_sub_f32_e32 v146, v149, v144
	v_sub_f32_e32 v147, v148, v144
	v_sub_f32_e32 v148, v151, v144
	v_sub_f32_e32 v149, v150, v144
	v_pk_fma_f32 v[134:135], v[94:95], v[134:135], v[98:99]
	v_pk_fma_f32 v[136:137], v[96:97], v[136:137], v[100:101]
	v_pk_mul_f32 v[148:149], v[144:145], v[148:149] op_sel:[1,0]
	v_pk_mul_f32 v[146:147], v[144:145], v[146:147] op_sel:[1,0]
	v_pk_fma_f32 v[148:149], v[88:89], v[148:149], v[92:93]
	v_pk_fma_f32 v[146:147], v[86:87], v[146:147], v[90:91]
	v_pk_fma_f32 v[76:77], v[136:137], s[18:19], v[76:77] op_sel_hi:[1,0,1]
	v_pk_fma_f32 v[74:75], v[134:135], s[18:19], v[74:75] op_sel_hi:[1,0,1]
	v_pk_fma_f32 v[134:135], v[148:149], s[18:19], v[64:65] op_sel_hi:[1,0,1]
	v_pk_fma_f32 v[64:65], v[146:147], s[18:19], v[62:63] op_sel_hi:[1,0,1]
	v_pk_mov_b32 v[62:63], v[74:75], v[76:77] op_sel:[1,0]
	v_mov_b32_e32 v136, v74
	v_mov_b32_e32 v137, v77
	v_pk_add_f32 v[136:137], v[62:63], v[136:137]
	v_pk_mul_f32 v[62:63], v[76:77], v[76:77]
	v_pk_mul_f32 v[148:149], v[74:75], v[74:75]
	v_lshl_add_u64 v[142:143], v[200:201], 0, v[142:143]
	v_pk_mov_b32 v[150:151], v[148:149], v[62:63] op_sel:[1,0]
	v_mov_b32_e32 v149, v63
	v_pk_add_f32 v[62:63], v[150:151], v[148:149]
	v_add_f32_e32 v146, v64, v65
	v_pk_add_f32 v[148:149], v[62:63], v[62:63] op_sel_hi:[0,1]
	v_mul_f32_e32 v62, v64, v64
	v_pk_fma_f32 v[150:151], v[64:65], v[64:65], v[62:63] op_sel_hi:[1,1,0]
	v_cvt_pk_f16_f32 v62, v74, v75
	v_cvt_pk_f16_f32 v63, v76, v77
	v_cvt_pk_f16_f32 v64, v64, v65
	v_cvt_pk_f16_f32 v65, v134, v135
	global_store_dwordx4 v[142:143], v[62:65], off
	s_waitcnt vmcnt(7)
	v_cvt_f32_f16_sdwa v75, v214 dst_sel:DWORD dst_unused:UNUSED_PAD src0_sel:WORD_1
	v_cvt_f32_f16_e32 v74, v214
	v_cvt_f32_f16_sdwa v63, v212 dst_sel:DWORD dst_unused:UNUSED_PAD src0_sel:WORD_1
	v_cvt_f32_f16_e32 v62, v212
	v_cvt_f32_f16_sdwa v65, v213 dst_sel:DWORD dst_unused:UNUSED_PAD src0_sel:WORD_1
	v_cvt_f32_f16_e32 v64, v213
	v_cvt_f32_f16_sdwa v77, v215 dst_sel:DWORD dst_unused:UNUSED_PAD src0_sel:WORD_1
	v_cvt_f32_f16_e32 v76, v215
	v_sub_f32_e32 v62, v62, v144
	v_sub_f32_e32 v63, v63, v144
	v_sub_f32_e32 v64, v64, v144
	v_sub_f32_e32 v65, v65, v144
	v_pk_mul_f32 v[64:65], v[144:145], v[64:65] op_sel:[1,0]
	v_pk_mul_f32 v[62:63], v[144:145], v[62:63] op_sel:[1,0]
	v_sub_f32_e32 v74, v74, v144
	v_sub_f32_e32 v75, v75, v144
	v_sub_f32_e32 v76, v76, v144
	v_sub_f32_e32 v77, v77, v144
	v_pk_fma_f32 v[62:63], v[78:79], v[62:63], v[82:83]
	v_pk_fma_f32 v[64:65], v[80:81], v[64:65], v[84:85]
	v_pk_mul_f32 v[76:77], v[144:145], v[76:77] op_sel:[1,0]
	v_pk_mul_f32 v[74:75], v[144:145], v[74:75] op_sel:[1,0]
	v_pk_fma_f32 v[76:77], v[68:69], v[76:77], v[72:73]
	v_pk_fma_f32 v[74:75], v[66:67], v[74:75], v[70:71]
	v_pk_fma_f32 v[60:61], v[64:65], s[18:19], v[60:61] op_sel_hi:[1,0,1]
	v_pk_fma_f32 v[58:59], v[62:63], s[18:19], v[58:59] op_sel_hi:[1,0,1]
	v_pk_fma_f32 v[62:63], v[76:77], s[18:19], v[56:57] op_sel_hi:[1,0,1]
	v_pk_fma_f32 v[56:57], v[74:75], s[18:19], v[54:55] op_sel_hi:[1,0,1]
	v_pk_mov_b32 v[54:55], v[58:59], v[60:61] op_sel:[1,0]
	v_mov_b32_e32 v64, v58
	v_mov_b32_e32 v65, v61
	v_pk_add_f32 v[64:65], v[54:55], v[64:65]
	v_mul_f32_e32 v54, v58, v58
	v_pk_fma_f32 v[74:75], v[58:59], v[58:59], v[54:55] op_sel_hi:[1,1,0]
	v_mul_f32_e32 v54, v60, v60
	v_pk_fma_f32 v[76:77], v[60:61], v[60:61], v[54:55] op_sel_hi:[1,1,0]
	v_mul_f32_e32 v54, v62, v62
	v_add_f32_e32 v152, v56, v57
	v_mul_f32_e32 v147, v56, v56
	v_mul_f32_e32 v140, v57, v57
	v_pk_fma_f32 v[138:139], v[62:63], v[62:63], v[54:55] op_sel_hi:[1,1,0]
	v_cvt_pk_f16_f32 v54, v58, v59
	v_cvt_pk_f16_f32 v55, v60, v61
	v_cvt_pk_f16_f32 v56, v56, v57
	v_cvt_pk_f16_f32 v57, v62, v63
	v_mul_f32_e32 v1, v135, v135
	global_store_dwordx4 v[142:143], v[54:57], off offset:256
	v_mul_f32_e32 v153, v134, v134
	v_mov_b32_e32 v150, v62
	v_pk_add_f32 v[54:55], v[64:65], v[64:65] op_sel:[0,1] op_sel_hi:[1,0]
	v_mov_b32_e32 v148, v63
	v_mov_b32_e32 v55, v1
	v_pk_add_f32 v[58:59], v[136:137], v[136:137] op_sel:[0,1] op_sel_hi:[1,0]
	v_pk_add_f32 v[54:55], v[152:153], v[54:55]
	v_pk_add_f32 v[56:57], v[150:151], v[148:149]
	v_mov_b32_e32 v74, v134
	v_mov_b32_e32 v76, v135
	v_mov_b32_e32 v59, v140
	v_pk_add_f32 v[54:55], v[54:55], v[56:57]
	v_pk_add_f32 v[56:57], v[74:75], v[76:77]
	v_pk_add_f32 v[58:59], v[146:147], v[58:59]
	v_mov_b32_e32 v1, v139
	v_pk_add_f32 v[56:57], v[58:59], v[56:57]
	s_nop 0
	v_pk_add_f32 v[56:57], v[56:57], v[0:1]
	s_nop 0
	v_pk_add_f32 v[54:55], v[54:55], v[56:57]
	ds_bpermute_b32 v56, v227, v54
	ds_bpermute_b32 v57, v227, v55
	s_waitcnt lgkmcnt(0)
	v_pk_add_f32 v[54:55], v[54:55], v[56:57]
	ds_bpermute_b32 v56, v226, v54
	ds_bpermute_b32 v57, v226, v55
	s_and_saveexec_b64 s[22:23], s[36:37]
	s_cbranch_execz .LBB0_1147
	s_waitcnt lgkmcnt(0)
	v_pk_add_f32 v[54:55], v[54:55], v[56:57]
	v_lshlrev_b64 v[56:57], 7, v[132:133]
	v_lshl_add_u64 v[56:57], s[44:45], 0, v[56:57]
	v_lshl_add_u64 v[56:57], vcc, 3, v[56:57]
	s_lshl_b32 s58, s71, 3
	v_lshl_add_u64 v[56:57], v[56:57], 0, s[58:59]
	global_store_dwordx2 v[56:57], v[54:55], off
; #define PG8_LAS __attribute__((address_space(3)))
;     __device__ __forceinline__ void operator()(const f32x4 (&acc)[2][2][4][2], const Unit& u, int ui, int wr, int wc, int fr, int fq) const {
;     ...
;                 for (int bj = 0; bj < 2; ++bj) rr[m][bj] = *(const bf16x8*)(R + (size_t)(row0 + ai * HALF + m * 16) * ldc + col0 + bj * HALF);
;             __builtin_amdgcn_sched_barrier(0); }
; #pragma unroll
;             for (int m = 0; m < 4; ++m) { const int row = row0 + ai * HALF + m * 16; const size_t off = (size_t)row * ldc + col0;
;                 float mu = 0.f, rs = 1.f; if (FOLD) { const f32x2_t ms = ((const PG8_LAS f32x2_t*)tb)[pslot + ai * HALF + wr * 64 + m * 16 + fr]; mu = ms.x; rs = ms.y; }
;                 float ssum = 0.f, ssq = 0.f;
; #pragma unroll
;                 for (int bj = 0; bj < 2; ++bj) { f32x4 v0 = acc[ai][bj][m][0], v1 = acc[ai][bj][m][1];
;                     if (FOLD && MODE != 2) { v0 = (v0 - mu * cv[bj][0]) * rs + bv[bj][0]; v1 = (v1 - mu * cv[bj][1]) * rs + bv[bj][1]; }
;                     if (MODE == 0) { v0 = v0 * sc; v1 = v1 * sc; }
;                     if (MODE == 1) { v0 = __builtin_elementwise_max(v0, (f32x4){0.f, 0.f, 0.f, 0.f}); v1 = __builtin_elementwise_max(v1, (f32x4){0.f, 0.f, 0.f, 0.f}); v0 = v0 * v0; v1 = v1 * v1; }
;                     if (MODE == 2) { const bf16x8 r = rr[m][bj];
;                         f32x4 h0 = (f32x4){(float)r[0], (float)r[1], (float)r[2], (float)r[3]}, h1 = (f32x4){(float)r[4], (float)r[5], (float)r[6], (float)r[7]};
;                         if (FOLD) { h0 = (h0 - mu) * rs * cv[bj][0] + bv[bj][0]; h1 = (h1 - mu) * rs * cv[bj][1] + bv[bj][1]; }
;                         v0 = v0 + alpha * h0; v1 = v1 + alpha * h1;
;                         ssum += (v0[0] + v0[1]) + (v0[2] + v0[3]) + (v1[0] + v1[1]) + (v1[2] + v1[3]);
;                         ssq += (v0[0] * v0[0] + v0[1] * v0[1]) + (v0[2] * v0[2] + v0[3] * v0[3]) + (v1[0] * v1[0] + v1[1] * v1[1]) + (v1[2] * v1[2] + v1[3] * v1[3]); }
;                     u32x4 w; w.x = pk2h(v0[0], v0[1]); w.y = pk2h(v0[2], v0[3]); w.z = pk2h(v1[0], v1[1]); w.w = pk2h(v1[2], v1[3]);
;                     if (MODE == 0 && hm) { const int cc = col0 + bj * HALF; *(u32x4*)(base + ((size_t)(row >> 11) * 16 + (cc >> 6)) * 131072 + (size_t)(row & 2047) * 64 + (cc & 63)) = w; }
;                     else *(u32x4*)(base + off + bj * HALF) = w; }
.LBB0_1147:
	s_or_b64 exec, exec, s[22:23]
	s_waitcnt lgkmcnt(0)
	ds_read_b64 v[56:57], v228 offset:1152
	s_waitcnt vmcnt(7)
	v_cvt_f32_f16_sdwa v1, v182 dst_sel:DWORD dst_unused:UNUSED_PAD src0_sel:WORD_1
	v_cvt_f32_f16_e32 v58, v182
	v_cvt_f32_f16_sdwa v60, v183 dst_sel:DWORD dst_unused:UNUSED_PAD src0_sel:WORD_1
	v_cvt_f32_f16_e32 v62, v183
	v_cvt_f32_f16_sdwa v63, v184 dst_sel:DWORD dst_unused:UNUSED_PAD src0_sel:WORD_1
	v_cvt_f32_f16_e32 v64, v184
	v_cvt_f32_f16_sdwa v65, v185 dst_sel:DWORD dst_unused:UNUSED_PAD src0_sel:WORD_1
	v_cvt_f32_f16_e32 v74, v185
	s_waitcnt lgkmcnt(0)
	v_sub_f32_e32 v59, v1, v56
	v_sub_f32_e32 v61, v60, v56
	v_sub_f32_e32 v58, v58, v56
	v_sub_f32_e32 v60, v62, v56
	v_pk_mul_f32 v[60:61], v[56:57], v[60:61] op_sel:[1,0]
	v_pk_mul_f32 v[58:59], v[56:57], v[58:59] op_sel:[1,0]
	v_sub_f32_e32 v63, v63, v56
	v_sub_f32_e32 v65, v65, v56
	v_sub_f32_e32 v62, v64, v56
	v_sub_f32_e32 v64, v74, v56
	v_pk_fma_f32 v[58:59], v[94:95], v[58:59], v[98:99]
	v_pk_fma_f32 v[60:61], v[96:97], v[60:61], v[100:101]
	v_pk_mul_f32 v[64:65], v[56:57], v[64:65] op_sel:[1,0]
	v_pk_mul_f32 v[62:63], v[56:57], v[62:63] op_sel:[1,0]
	v_pk_fma_f32 v[64:65], v[88:89], v[64:65], v[92:93]
	v_pk_fma_f32 v[62:63], v[86:87], v[62:63], v[90:91]
	v_pk_fma_f32 v[52:53], v[60:61], s[18:19], v[52:53] op_sel_hi:[1,0,1]
	v_pk_fma_f32 v[50:51], v[58:59], s[18:19], v[50:51] op_sel_hi:[1,0,1]
	v_pk_fma_f32 v[58:59], v[64:65], s[18:19], v[48:49] op_sel_hi:[1,0,1]
	v_pk_fma_f32 v[48:49], v[62:63], s[18:19], v[46:47] op_sel_hi:[1,0,1]
	v_pk_mov_b32 v[46:47], v[50:51], v[52:53] op_sel:[1,0]
	v_mov_b32_e32 v60, v50
	v_mov_b32_e32 v61, v53
	v_pk_add_f32 v[60:61], v[46:47], v[60:61]
	v_pk_mul_f32 v[46:47], v[52:53], v[52:53]
	v_pk_mul_f32 v[64:65], v[50:51], v[50:51]
	v_lshlrev_b64 v[54:55], 10, v[130:131]
	v_pk_mov_b32 v[74:75], v[64:65], v[46:47] op_sel:[1,0]
	v_mov_b32_e32 v65, v47
	v_pk_add_f32 v[46:47], v[74:75], v[64:65]
	v_lshl_add_u64 v[54:55], v[54:55], 1, v[200:201]
	v_pk_add_f32 v[64:65], v[46:47], v[46:47] op_sel_hi:[0,1]
	v_mul_f32_e32 v46, v48, v48
	v_add_f32_e32 v62, v48, v49
	v_pk_fma_f32 v[74:75], v[48:49], v[48:49], v[46:47] op_sel_hi:[1,1,0]
	v_cvt_pk_f16_f32 v46, v50, v51
	v_cvt_pk_f16_f32 v47, v52, v53
	v_cvt_pk_f16_f32 v48, v48, v49
	v_cvt_pk_f16_f32 v49, v58, v59
	global_store_dwordx4 v[54:55], v[46:49], off
	s_waitcnt vmcnt(7)
	v_cvt_f32_f16_e32 v50, v187
	v_cvt_f32_f16_sdwa v51, v188 dst_sel:DWORD dst_unused:UNUSED_PAD src0_sel:WORD_1
	v_cvt_f32_f16_sdwa v46, v186 dst_sel:DWORD dst_unused:UNUSED_PAD src0_sel:WORD_1
	v_cvt_f32_f16_e32 v48, v186
	v_cvt_f32_f16_sdwa v49, v187 dst_sel:DWORD dst_unused:UNUSED_PAD src0_sel:WORD_1
	v_cvt_f32_f16_e32 v52, v188
	v_cvt_f32_f16_sdwa v53, v189 dst_sel:DWORD dst_unused:UNUSED_PAD src0_sel:WORD_1
	v_cvt_f32_f16_e32 v63, v189
	v_sub_f32_e32 v47, v46, v56
	v_sub_f32_e32 v49, v49, v56
	v_sub_f32_e32 v46, v48, v56
	v_sub_f32_e32 v48, v50, v56
	v_pk_mul_f32 v[48:49], v[56:57], v[48:49] op_sel:[1,0]
	v_pk_mul_f32 v[46:47], v[56:57], v[46:47] op_sel:[1,0]
	v_sub_f32_e32 v51, v51, v56
	v_sub_f32_e32 v53, v53, v56
	v_sub_f32_e32 v50, v52, v56
	v_sub_f32_e32 v52, v63, v56
	v_pk_fma_f32 v[46:47], v[78:79], v[46:47], v[82:83]
	v_pk_fma_f32 v[48:49], v[80:81], v[48:49], v[84:85]
	v_pk_mul_f32 v[52:53], v[56:57], v[52:53] op_sel:[1,0]
	v_pk_mul_f32 v[50:51], v[56:57], v[50:51] op_sel:[1,0]
	v_pk_fma_f32 v[52:53], v[68:69], v[52:53], v[72:73]
	v_pk_fma_f32 v[50:51], v[66:67], v[50:51], v[70:71]
	v_pk_fma_f32 v[44:45], v[48:49], s[18:19], v[44:45] op_sel_hi:[1,0,1]
	v_pk_fma_f32 v[42:43], v[46:47], s[18:19], v[42:43] op_sel_hi:[1,0,1]
	v_pk_fma_f32 v[46:47], v[52:53], s[18:19], v[40:41] op_sel_hi:[1,0,1]
	v_pk_fma_f32 v[40:41], v[50:51], s[18:19], v[38:39] op_sel_hi:[1,0,1]
	v_pk_mov_b32 v[38:39], v[42:43], v[44:45] op_sel:[1,0]
	v_mov_b32_e32 v48, v42
	v_mov_b32_e32 v49, v45
	v_pk_add_f32 v[48:49], v[38:39], v[48:49]
	v_mul_f32_e32 v38, v42, v42
	v_pk_fma_f32 v[50:51], v[42:43], v[42:43], v[38:39] op_sel_hi:[1,1,0]
	v_mul_f32_e32 v38, v44, v44
	v_pk_fma_f32 v[52:53], v[44:45], v[44:45], v[38:39] op_sel_hi:[1,1,0]
	v_mul_f32_e32 v38, v46, v46
	v_add_f32_e32 v76, v40, v41
	v_mul_f32_e32 v63, v40, v40
	v_mul_f32_e32 v118, v41, v41
	v_pk_fma_f32 v[56:57], v[46:47], v[46:47], v[38:39] op_sel_hi:[1,1,0]
	v_cvt_pk_f16_f32 v38, v42, v43
	v_cvt_pk_f16_f32 v39, v44, v45
	v_cvt_pk_f16_f32 v40, v40, v41
	v_cvt_pk_f16_f32 v41, v46, v47
	v_mul_f32_e32 v1, v59, v59
	global_store_dwordx4 v[54:55], v[38:41], off offset:256
	v_mul_f32_e32 v77, v58, v58
	v_mov_b32_e32 v74, v46
	v_pk_add_f32 v[38:39], v[48:49], v[48:49] op_sel:[0,1] op_sel_hi:[1,0]
	v_mov_b32_e32 v64, v47
	v_mov_b32_e32 v39, v1
	v_pk_add_f32 v[42:43], v[60:61], v[60:61] op_sel:[0,1] op_sel_hi:[1,0]
	v_pk_add_f32 v[38:39], v[76:77], v[38:39]
	v_pk_add_f32 v[40:41], v[74:75], v[64:65]
	v_mov_b32_e32 v50, v58
	v_mov_b32_e32 v52, v59
	v_mov_b32_e32 v43, v118
	v_pk_add_f32 v[38:39], v[38:39], v[40:41]
	v_pk_add_f32 v[40:41], v[50:51], v[52:53]
	v_pk_add_f32 v[42:43], v[62:63], v[42:43]
	v_mov_b32_e32 v1, v57
	v_pk_add_f32 v[40:41], v[42:43], v[40:41]
	s_nop 0
	v_pk_add_f32 v[40:41], v[40:41], v[0:1]
	s_nop 0
	v_pk_add_f32 v[38:39], v[38:39], v[40:41]
	ds_bpermute_b32 v40, v227, v38
	ds_bpermute_b32 v41, v227, v39
	s_waitcnt lgkmcnt(0)
	v_pk_add_f32 v[38:39], v[38:39], v[40:41]
	ds_bpermute_b32 v40, v226, v38
	ds_bpermute_b32 v41, v226, v39
	s_and_saveexec_b64 s[22:23], s[36:37]
	s_cbranch_execz .LBB0_1149
	s_waitcnt lgkmcnt(0)
	v_pk_add_f32 v[38:39], v[38:39], v[40:41]
	v_lshlrev_b64 v[40:41], 7, v[130:131]
	v_lshl_add_u64 v[40:41], s[44:45], 0, v[40:41]
	v_lshl_add_u64 v[40:41], vcc, 3, v[40:41]
	s_lshl_b32 s58, s71, 3
	v_lshl_add_u64 v[40:41], v[40:41], 0, s[58:59]
	global_store_dwordx2 v[40:41], v[38:39], off
; #define PG8_LAS __attribute__((address_space(3)))
;     __device__ __forceinline__ void operator()(const f32x4 (&acc)[2][2][4][2], const Unit& u, int ui, int wr, int wc, int fr, int fq) const {
;     ...
;                 for (int bj = 0; bj < 2; ++bj) rr[m][bj] = *(const bf16x8*)(R + (size_t)(row0 + ai * HALF + m * 16) * ldc + col0 + bj * HALF);
;             __builtin_amdgcn_sched_barrier(0); }
; #pragma unroll
;             for (int m = 0; m < 4; ++m) { const int row = row0 + ai * HALF + m * 16; const size_t off = (size_t)row * ldc + col0;
;                 float mu = 0.f, rs = 1.f; if (FOLD) { const f32x2_t ms = ((const PG8_LAS f32x2_t*)tb)[pslot + ai * HALF + wr * 64 + m * 16 + fr]; mu = ms.x; rs = ms.y; }
;                 float ssum = 0.f, ssq = 0.f;
; #pragma unroll
;                 for (int bj = 0; bj < 2; ++bj) { f32x4 v0 = acc[ai][bj][m][0], v1 = acc[ai][bj][m][1];
;                     if (FOLD && MODE != 2) { v0 = (v0 - mu * cv[bj][0]) * rs + bv[bj][0]; v1 = (v1 - mu * cv[bj][1]) * rs + bv[bj][1]; }
;                     if (MODE == 0) { v0 = v0 * sc; v1 = v1 * sc; }
;                     if (MODE == 1) { v0 = __builtin_elementwise_max(v0, (f32x4){0.f, 0.f, 0.f, 0.f}); v1 = __builtin_elementwise_max(v1, (f32x4){0.f, 0.f, 0.f, 0.f}); v0 = v0 * v0; v1 = v1 * v1; }
;                     if (MODE == 2) { const bf16x8 r = rr[m][bj];
;                         f32x4 h0 = (f32x4){(float)r[0], (float)r[1], (float)r[2], (float)r[3]}, h1 = (f32x4){(float)r[4], (float)r[5], (float)r[6], (float)r[7]};
;                         if (FOLD) { h0 = (h0 - mu) * rs * cv[bj][0] + bv[bj][0]; h1 = (h1 - mu) * rs * cv[bj][1] + bv[bj][1]; }
;                         v0 = v0 + alpha * h0; v1 = v1 + alpha * h1;
;                         ssum += (v0[0] + v0[1]) + (v0[2] + v0[3]) + (v1[0] + v1[1]) + (v1[2] + v1[3]);
;                         ssq += (v0[0] * v0[0] + v0[1] * v0[1]) + (v0[2] * v0[2] + v0[3] * v0[3]) + (v1[0] * v1[0] + v1[1] * v1[1]) + (v1[2] * v1[2] + v1[3] * v1[3]); }
;                     u32x4 w; w.x = pk2h(v0[0], v0[1]); w.y = pk2h(v0[2], v0[3]); w.z = pk2h(v1[0], v1[1]); w.w = pk2h(v1[2], v1[3]);
;                     if (MODE == 0 && hm) { const int cc = col0 + bj * HALF; *(u32x4*)(base + ((size_t)(row >> 11) * 16 + (cc >> 6)) * 131072 + (size_t)(row & 2047) * 64 + (cc & 63)) = w; }
;                     else *(u32x4*)(base + off + bj * HALF) = w; }
.LBB0_1149:
	s_or_b64 exec, exec, s[22:23]
	s_waitcnt lgkmcnt(0)
	ds_read_b64 v[40:41], v228 offset:1280
	s_waitcnt vmcnt(7)
	v_cvt_f32_f16_sdwa v1, v162 dst_sel:DWORD dst_unused:UNUSED_PAD src0_sel:WORD_1
	v_cvt_f32_f16_e32 v42, v162
	v_cvt_f32_f16_sdwa v44, v163 dst_sel:DWORD dst_unused:UNUSED_PAD src0_sel:WORD_1
	v_cvt_f32_f16_e32 v46, v163
	v_cvt_f32_f16_sdwa v47, v164 dst_sel:DWORD dst_unused:UNUSED_PAD src0_sel:WORD_1
	v_cvt_f32_f16_e32 v48, v164
	v_cvt_f32_f16_sdwa v49, v165 dst_sel:DWORD dst_unused:UNUSED_PAD src0_sel:WORD_1
	v_cvt_f32_f16_e32 v50, v165
	s_waitcnt lgkmcnt(0)
	v_sub_f32_e32 v43, v1, v40
	v_sub_f32_e32 v45, v44, v40
	v_sub_f32_e32 v42, v42, v40
	v_sub_f32_e32 v44, v46, v40
	v_pk_mul_f32 v[44:45], v[40:41], v[44:45] op_sel:[1,0]
	v_pk_mul_f32 v[42:43], v[40:41], v[42:43] op_sel:[1,0]
	v_sub_f32_e32 v47, v47, v40
	v_sub_f32_e32 v49, v49, v40
	v_sub_f32_e32 v46, v48, v40
	v_sub_f32_e32 v48, v50, v40
	v_pk_fma_f32 v[42:43], v[94:95], v[42:43], v[98:99]
	v_pk_fma_f32 v[44:45], v[96:97], v[44:45], v[100:101]
	v_pk_mul_f32 v[48:49], v[40:41], v[48:49] op_sel:[1,0]
	v_pk_mul_f32 v[46:47], v[40:41], v[46:47] op_sel:[1,0]
	v_pk_fma_f32 v[48:49], v[88:89], v[48:49], v[92:93]
	v_pk_fma_f32 v[46:47], v[86:87], v[46:47], v[90:91]
	v_pk_fma_f32 v[36:37], v[44:45], s[18:19], v[36:37] op_sel_hi:[1,0,1]
	v_pk_fma_f32 v[34:35], v[42:43], s[18:19], v[34:35] op_sel_hi:[1,0,1]
	v_pk_fma_f32 v[42:43], v[48:49], s[18:19], v[32:33] op_sel_hi:[1,0,1]
	v_pk_fma_f32 v[32:33], v[46:47], s[18:19], v[30:31] op_sel_hi:[1,0,1]
	v_pk_mov_b32 v[30:31], v[34:35], v[36:37] op_sel:[1,0]
	v_mov_b32_e32 v44, v34
	v_mov_b32_e32 v45, v37
	v_pk_add_f32 v[44:45], v[30:31], v[44:45]
	v_pk_mul_f32 v[30:31], v[36:37], v[36:37]
	v_pk_mul_f32 v[48:49], v[34:35], v[34:35]
	v_lshlrev_b64 v[38:39], 10, v[128:129]
	v_pk_mov_b32 v[50:51], v[48:49], v[30:31] op_sel:[1,0]
	v_mov_b32_e32 v49, v31
	v_pk_add_f32 v[30:31], v[50:51], v[48:49]
	v_lshl_add_u64 v[38:39], v[38:39], 1, v[200:201]
	v_pk_add_f32 v[48:49], v[30:31], v[30:31] op_sel_hi:[0,1]
	v_mul_f32_e32 v30, v32, v32
	v_add_f32_e32 v46, v32, v33
	v_pk_fma_f32 v[50:51], v[32:33], v[32:33], v[30:31] op_sel_hi:[1,1,0]
	v_cvt_pk_f16_f32 v30, v34, v35
	v_cvt_pk_f16_f32 v31, v36, v37
	v_cvt_pk_f16_f32 v32, v32, v33
	v_cvt_pk_f16_f32 v33, v42, v43
	global_store_dwordx4 v[38:39], v[30:33], off
	s_waitcnt vmcnt(7)
	v_cvt_f32_f16_e32 v34, v167
	v_cvt_f32_f16_sdwa v35, v168 dst_sel:DWORD dst_unused:UNUSED_PAD src0_sel:WORD_1
	v_cvt_f32_f16_sdwa v30, v166 dst_sel:DWORD dst_unused:UNUSED_PAD src0_sel:WORD_1
	v_cvt_f32_f16_e32 v32, v166
	v_cvt_f32_f16_sdwa v33, v167 dst_sel:DWORD dst_unused:UNUSED_PAD src0_sel:WORD_1
	v_cvt_f32_f16_e32 v36, v168
	v_cvt_f32_f16_sdwa v37, v169 dst_sel:DWORD dst_unused:UNUSED_PAD src0_sel:WORD_1
	v_cvt_f32_f16_e32 v47, v169
	v_sub_f32_e32 v31, v30, v40
	v_sub_f32_e32 v33, v33, v40
	v_sub_f32_e32 v30, v32, v40
	v_sub_f32_e32 v32, v34, v40
	v_pk_mul_f32 v[32:33], v[40:41], v[32:33] op_sel:[1,0]
	v_pk_mul_f32 v[30:31], v[40:41], v[30:31] op_sel:[1,0]
	v_sub_f32_e32 v35, v35, v40
	v_sub_f32_e32 v37, v37, v40
	v_sub_f32_e32 v34, v36, v40
	v_sub_f32_e32 v36, v47, v40
	v_pk_fma_f32 v[30:31], v[78:79], v[30:31], v[82:83]
	v_pk_fma_f32 v[32:33], v[80:81], v[32:33], v[84:85]
	v_pk_mul_f32 v[36:37], v[40:41], v[36:37] op_sel:[1,0]
	v_pk_mul_f32 v[34:35], v[40:41], v[34:35] op_sel:[1,0]
	v_pk_fma_f32 v[36:37], v[68:69], v[36:37], v[72:73]
	v_pk_fma_f32 v[34:35], v[66:67], v[34:35], v[70:71]
	v_pk_fma_f32 v[28:29], v[32:33], s[18:19], v[28:29] op_sel_hi:[1,0,1]
	v_pk_fma_f32 v[26:27], v[30:31], s[18:19], v[26:27] op_sel_hi:[1,0,1]
	v_pk_fma_f32 v[30:31], v[36:37], s[18:19], v[24:25] op_sel_hi:[1,0,1]
	v_pk_fma_f32 v[24:25], v[34:35], s[18:19], v[22:23] op_sel_hi:[1,0,1]
	v_pk_mov_b32 v[22:23], v[26:27], v[28:29] op_sel:[1,0]
	v_mov_b32_e32 v32, v26
	v_mov_b32_e32 v33, v29
	v_pk_add_f32 v[32:33], v[22:23], v[32:33]
	v_mul_f32_e32 v22, v26, v26
	v_pk_fma_f32 v[34:35], v[26:27], v[26:27], v[22:23] op_sel_hi:[1,1,0]
	v_mul_f32_e32 v22, v28, v28
	v_pk_fma_f32 v[36:37], v[28:29], v[28:29], v[22:23] op_sel_hi:[1,1,0]
	v_mul_f32_e32 v22, v30, v30
	v_add_f32_e32 v52, v24, v25
	v_mul_f32_e32 v47, v24, v24
	v_mul_f32_e32 v54, v25, v25
	v_pk_fma_f32 v[40:41], v[30:31], v[30:31], v[22:23] op_sel_hi:[1,1,0]
	v_cvt_pk_f16_f32 v22, v26, v27
	v_cvt_pk_f16_f32 v23, v28, v29
	v_cvt_pk_f16_f32 v24, v24, v25
	v_cvt_pk_f16_f32 v25, v30, v31
	v_mul_f32_e32 v1, v43, v43
	global_store_dwordx4 v[38:39], v[22:25], off offset:256
	v_mul_f32_e32 v53, v42, v42
	v_mov_b32_e32 v50, v30
	v_pk_add_f32 v[22:23], v[32:33], v[32:33] op_sel:[0,1] op_sel_hi:[1,0]
	v_mov_b32_e32 v48, v31
	v_mov_b32_e32 v23, v1
	v_pk_add_f32 v[26:27], v[44:45], v[44:45] op_sel:[0,1] op_sel_hi:[1,0]
	v_pk_add_f32 v[22:23], v[52:53], v[22:23]
	v_pk_add_f32 v[24:25], v[50:51], v[48:49]
	v_mov_b32_e32 v34, v42
	v_mov_b32_e32 v36, v43
	v_mov_b32_e32 v27, v54
	v_pk_add_f32 v[22:23], v[22:23], v[24:25]
	v_pk_add_f32 v[24:25], v[34:35], v[36:37]
	v_pk_add_f32 v[26:27], v[46:47], v[26:27]
	v_mov_b32_e32 v1, v41
	v_pk_add_f32 v[24:25], v[26:27], v[24:25]
	s_nop 0
	v_pk_add_f32 v[24:25], v[24:25], v[0:1]
	s_nop 0
	v_pk_add_f32 v[22:23], v[22:23], v[24:25]
	ds_bpermute_b32 v24, v227, v22
	ds_bpermute_b32 v25, v227, v23
	s_waitcnt lgkmcnt(0)
	v_pk_add_f32 v[22:23], v[22:23], v[24:25]
	ds_bpermute_b32 v24, v226, v22
	ds_bpermute_b32 v25, v226, v23
	s_and_saveexec_b64 s[22:23], s[36:37]
	s_cbranch_execz .LBB0_1151
	s_waitcnt lgkmcnt(0)
	v_pk_add_f32 v[22:23], v[22:23], v[24:25]
	v_lshlrev_b64 v[24:25], 7, v[128:129]
	v_lshl_add_u64 v[24:25], s[44:45], 0, v[24:25]
	v_lshl_add_u64 v[24:25], vcc, 3, v[24:25]
	s_lshl_b32 s58, s71, 3
	v_lshl_add_u64 v[24:25], v[24:25], 0, s[58:59]
	global_store_dwordx2 v[24:25], v[22:23], off
; #define PG8_LAS __attribute__((address_space(3)))
;     __device__ __forceinline__ void operator()(const f32x4 (&acc)[2][2][4][2], const Unit& u, int ui, int wr, int wc, int fr, int fq) const {
;     ...
;                 for (int bj = 0; bj < 2; ++bj) rr[m][bj] = *(const bf16x8*)(R + (size_t)(row0 + ai * HALF + m * 16) * ldc + col0 + bj * HALF);
;             __builtin_amdgcn_sched_barrier(0); }
; #pragma unroll
;             for (int m = 0; m < 4; ++m) { const int row = row0 + ai * HALF + m * 16; const size_t off = (size_t)row * ldc + col0;
;                 float mu = 0.f, rs = 1.f; if (FOLD) { const f32x2_t ms = ((const PG8_LAS f32x2_t*)tb)[pslot + ai * HALF + wr * 64 + m * 16 + fr]; mu = ms.x; rs = ms.y; }
;                 float ssum = 0.f, ssq = 0.f;
; #pragma unroll
;                 for (int bj = 0; bj < 2; ++bj) { f32x4 v0 = acc[ai][bj][m][0], v1 = acc[ai][bj][m][1];
;                     if (FOLD && MODE != 2) { v0 = (v0 - mu * cv[bj][0]) * rs + bv[bj][0]; v1 = (v1 - mu * cv[bj][1]) * rs + bv[bj][1]; }
;                     if (MODE == 0) { v0 = v0 * sc; v1 = v1 * sc; }
;                     if (MODE == 1) { v0 = __builtin_elementwise_max(v0, (f32x4){0.f, 0.f, 0.f, 0.f}); v1 = __builtin_elementwise_max(v1, (f32x4){0.f, 0.f, 0.f, 0.f}); v0 = v0 * v0; v1 = v1 * v1; }
;                     if (MODE == 2) { const bf16x8 r = rr[m][bj];
;                         f32x4 h0 = (f32x4){(float)r[0], (float)r[1], (float)r[2], (float)r[3]}, h1 = (f32x4){(float)r[4], (float)r[5], (float)r[6], (float)r[7]};
;                         if (FOLD) { h0 = (h0 - mu) * rs * cv[bj][0] + bv[bj][0]; h1 = (h1 - mu) * rs * cv[bj][1] + bv[bj][1]; }
;                         v0 = v0 + alpha * h0; v1 = v1 + alpha * h1;
;                         ssum += (v0[0] + v0[1]) + (v0[2] + v0[3]) + (v1[0] + v1[1]) + (v1[2] + v1[3]);
;                         ssq += (v0[0] * v0[0] + v0[1] * v0[1]) + (v0[2] * v0[2] + v0[3] * v0[3]) + (v1[0] * v1[0] + v1[1] * v1[1]) + (v1[2] * v1[2] + v1[3] * v1[3]); }
;                     u32x4 w; w.x = pk2h(v0[0], v0[1]); w.y = pk2h(v0[2], v0[3]); w.z = pk2h(v1[0], v1[1]); w.w = pk2h(v1[2], v1[3]);
;                     if (MODE == 0 && hm) { const int cc = col0 + bj * HALF; *(u32x4*)(base + ((size_t)(row >> 11) * 16 + (cc >> 6)) * 131072 + (size_t)(row & 2047) * 64 + (cc & 63)) = w; }
;                     else *(u32x4*)(base + off + bj * HALF) = w; }
.LBB0_1151:
	s_or_b64 exec, exec, s[22:23]
	s_waitcnt lgkmcnt(0)
	ds_read_b64 v[24:25], v228 offset:1408
	s_waitcnt vmcnt(7)
	v_cvt_f32_f16_sdwa v1, v154 dst_sel:DWORD dst_unused:UNUSED_PAD src0_sel:WORD_1
	v_cvt_f32_f16_e32 v26, v154
	v_cvt_f32_f16_sdwa v28, v155 dst_sel:DWORD dst_unused:UNUSED_PAD src0_sel:WORD_1
	v_cvt_f32_f16_e32 v30, v155
	v_cvt_f32_f16_sdwa v31, v156 dst_sel:DWORD dst_unused:UNUSED_PAD src0_sel:WORD_1
	v_cvt_f32_f16_e32 v32, v156
	v_cvt_f32_f16_sdwa v33, v157 dst_sel:DWORD dst_unused:UNUSED_PAD src0_sel:WORD_1
	v_cvt_f32_f16_e32 v34, v157
	s_waitcnt lgkmcnt(0)
	v_sub_f32_e32 v27, v1, v24
	v_sub_f32_e32 v29, v28, v24
	v_sub_f32_e32 v26, v26, v24
	v_sub_f32_e32 v28, v30, v24
	v_pk_mul_f32 v[28:29], v[24:25], v[28:29] op_sel:[1,0]
	v_pk_mul_f32 v[26:27], v[24:25], v[26:27] op_sel:[1,0]
	v_sub_f32_e32 v31, v31, v24
	v_sub_f32_e32 v33, v33, v24
	v_sub_f32_e32 v30, v32, v24
	v_sub_f32_e32 v32, v34, v24
	v_pk_fma_f32 v[26:27], v[94:95], v[26:27], v[98:99]
	v_pk_fma_f32 v[28:29], v[96:97], v[28:29], v[100:101]
	v_pk_mul_f32 v[32:33], v[24:25], v[32:33] op_sel:[1,0]
	v_pk_mul_f32 v[30:31], v[24:25], v[30:31] op_sel:[1,0]
	v_pk_fma_f32 v[32:33], v[88:89], v[32:33], v[92:93]
	v_pk_fma_f32 v[30:31], v[86:87], v[30:31], v[90:91]
	v_pk_fma_f32 v[20:21], v[28:29], s[18:19], v[20:21] op_sel_hi:[1,0,1]
	v_pk_fma_f32 v[18:19], v[26:27], s[18:19], v[18:19] op_sel_hi:[1,0,1]
	v_pk_fma_f32 v[26:27], v[32:33], s[18:19], v[12:13] op_sel_hi:[1,0,1]
	v_pk_fma_f32 v[12:13], v[30:31], s[18:19], v[10:11] op_sel_hi:[1,0,1]
	v_pk_mov_b32 v[10:11], v[18:19], v[20:21] op_sel:[1,0]
	v_mov_b32_e32 v28, v18
	v_mov_b32_e32 v29, v21
	v_pk_add_f32 v[28:29], v[10:11], v[28:29]
	v_pk_mul_f32 v[10:11], v[20:21], v[20:21]
	v_pk_mul_f32 v[32:33], v[18:19], v[18:19]
	s_waitcnt vmcnt(6)
	v_cvt_f32_f16_e32 v31, v103
	v_pk_mov_b32 v[34:35], v[32:33], v[10:11] op_sel:[1,0]
	v_mov_b32_e32 v33, v11
	v_pk_add_f32 v[10:11], v[34:35], v[32:33]
	v_cvt_f32_f16_sdwa v36, v105 dst_sel:DWORD dst_unused:UNUSED_PAD src0_sel:WORD_1
	v_pk_add_f32 v[32:33], v[10:11], v[10:11] op_sel_hi:[0,1]
	v_mul_f32_e32 v10, v12, v12
	v_pk_fma_f32 v[34:35], v[12:13], v[12:13], v[10:11] op_sel_hi:[1,1,0]
	v_cvt_pk_f16_f32 v10, v18, v19
	v_cvt_pk_f16_f32 v11, v20, v21
	v_cvt_f32_f16_sdwa v18, v102 dst_sel:DWORD dst_unused:UNUSED_PAD src0_sel:WORD_1
	v_cvt_f32_f16_e32 v20, v102
	v_cvt_f32_f16_sdwa v21, v103 dst_sel:DWORD dst_unused:UNUSED_PAD src0_sel:WORD_1
	v_cvt_f32_f16_sdwa v32, v104 dst_sel:DWORD dst_unused:UNUSED_PAD src0_sel:WORD_1
	v_cvt_f32_f16_e32 v34, v104
	v_cvt_f32_f16_e32 v40, v105
	v_sub_f32_e32 v19, v18, v24
	v_sub_f32_e32 v21, v21, v24
	v_sub_f32_e32 v18, v20, v24
	v_sub_f32_e32 v20, v31, v24
	v_pk_mul_f32 v[20:21], v[24:25], v[20:21] op_sel:[1,0]
	v_pk_mul_f32 v[18:19], v[24:25], v[18:19] op_sel:[1,0]
	v_sub_f32_e32 v39, v32, v24
	v_sub_f32_e32 v41, v36, v24
	v_sub_f32_e32 v38, v34, v24
	v_sub_f32_e32 v40, v40, v24
	v_pk_fma_f32 v[18:19], v[78:79], v[18:19], v[82:83]
	v_pk_fma_f32 v[20:21], v[80:81], v[20:21], v[84:85]
	v_pk_mul_f32 v[40:41], v[24:25], v[40:41] op_sel:[1,0]
	v_pk_mul_f32 v[24:25], v[24:25], v[38:39] op_sel:[1,0]
	v_pk_fma_f32 v[38:39], v[68:69], v[40:41], v[72:73]
	v_pk_fma_f32 v[24:25], v[66:67], v[24:25], v[70:71]
	v_pk_fma_f32 v[8:9], v[20:21], s[18:19], v[8:9] op_sel_hi:[1,0,1]
	v_pk_fma_f32 v[6:7], v[18:19], s[18:19], v[6:7] op_sel_hi:[1,0,1]
	v_pk_fma_f32 v[18:19], v[38:39], s[18:19], v[4:5] op_sel_hi:[1,0,1]
	v_pk_fma_f32 v[20:21], v[24:25], s[18:19], v[2:3] op_sel_hi:[1,0,1]
	v_pk_mov_b32 v[2:3], v[6:7], v[8:9] op_sel:[1,0]
	v_mov_b32_e32 v4, v6
	v_mov_b32_e32 v5, v9
	v_pk_add_f32 v[2:3], v[2:3], v[4:5]
	v_mul_f32_e32 v4, v6, v6
	v_pk_fma_f32 v[4:5], v[6:7], v[6:7], v[4:5] op_sel_hi:[1,1,0]
	v_mul_f32_e32 v40, v21, v21
	v_mul_f32_e32 v4, v8, v8
	v_pk_fma_f32 v[24:25], v[8:9], v[8:9], v[4:5] op_sel_hi:[1,1,0]
	v_mul_f32_e32 v4, v18, v18
	v_pk_fma_f32 v[38:39], v[18:19], v[18:19], v[4:5] op_sel_hi:[1,1,0]
	v_mov_b32_e32 v4, v26
	v_mov_b32_e32 v24, v27
	v_pk_add_f32 v[4:5], v[4:5], v[24:25]
	v_pk_add_f32 v[24:25], v[28:29], v[28:29] op_sel:[0,1] op_sel_hi:[1,0]
	v_add_f32_e32 v30, v12, v13
	v_mul_f32_e32 v1, v27, v27
	v_mul_f32_e32 v31, v20, v20
	v_pk_add_f32 v[2:3], v[2:3], v[2:3] op_sel:[0,1] op_sel_hi:[1,0]
	v_mov_b32_e32 v25, v40
	v_mul_f32_e32 v37, v26, v26
	v_add_f32_e32 v36, v20, v21
	v_mov_b32_e32 v3, v1
	v_mov_b32_e32 v34, v18
	v_mov_b32_e32 v32, v19
	v_pk_add_f32 v[24:25], v[30:31], v[24:25]
	v_pk_add_f32 v[2:3], v[36:37], v[2:3]
	v_pk_add_f32 v[32:33], v[34:35], v[32:33]
	v_pk_add_f32 v[4:5], v[24:25], v[4:5]
	v_mov_b32_e32 v1, v39
	v_pk_add_f32 v[2:3], v[2:3], v[32:33]
	v_pk_add_f32 v[4:5], v[4:5], v[0:1]
	v_lshlrev_b64 v[22:23], 10, v[126:127]
	v_pk_add_f32 v[2:3], v[2:3], v[4:5]
	ds_bpermute_b32 v4, v227, v2
	ds_bpermute_b32 v5, v227, v3
	v_lshl_add_u64 v[22:23], v[22:23], 1, v[200:201]
	v_cvt_pk_f16_f32 v12, v12, v13
	v_cvt_pk_f16_f32 v13, v26, v27
	v_cvt_pk_f16_f32 v6, v6, v7
	s_waitcnt lgkmcnt(0)
	v_pk_add_f32 v[2:3], v[2:3], v[4:5]
	ds_bpermute_b32 v4, v226, v2
	ds_bpermute_b32 v5, v226, v3
	v_cvt_pk_f16_f32 v7, v8, v9
	v_cvt_pk_f16_f32 v8, v20, v21
	v_cvt_pk_f16_f32 v9, v18, v19
	global_store_dwordx4 v[22:23], v[10:13], off
	global_store_dwordx4 v[22:23], v[6:9], off offset:256
	s_and_saveexec_b64 s[22:23], s[36:37]
	s_cbranch_execz .LBB0_1153
	s_waitcnt lgkmcnt(0)
	v_pk_add_f32 v[2:3], v[2:3], v[4:5]
	v_lshlrev_b64 v[4:5], 7, v[126:127]
	v_lshl_add_u64 v[4:5], s[44:45], 0, v[4:5]
	v_lshl_add_u64 v[4:5], vcc, 3, v[4:5]
	s_lshl_b32 s58, s71, 3
	v_lshl_add_u64 v[4:5], v[4:5], 0, s[58:59]
	global_store_dwordx2 v[4:5], v[2:3], off
